# lrubuf: LRU epilogue outputs buffered in registers, 4x4 lane-quad transpose (DPP) and stored as 8 dwordx4 per thread per tile (was 32 dword stores)
# baseline (speedup 1.0000x reference)
; #define MFMA16(a, b, c) __builtin_amdgcn_mfma_f32_16x16x32_bf16(a, b, c, 0, 0, 0)
; template <int EPI>
; __device__ __forceinline__ void gemm_tile(const Params& p, const EpiArgs& ea, const bf16_t* __restrict__ A, int lda,
;                                           const bf16_t* __restrict__ Bt, int K, int m0, int n0, char* smem) {
;     ...
;   const int srow = tid >> 3, sch = (tid & 7) * 8;
;   const bf16_t* ap = A + (size_t)(m0 + srow) * lda + sch;
;   const bf16_t* bp = Bt + (size_t)(n0 + srow) * K + sch;
;   const size_t a_step = (size_t)64 * lda, b_step = (size_t)64 * K;
;   uint4 ra[4], rb[2];
;   const int nk = K >> 6;
; #pragma unroll
;   for (int i = 0; i < 4; ++i) ra[i] = *(const uint4*)(ap + i * a_step);
; #pragma unroll
;   for (int i = 0; i < 2; ++i) rb[i] = *(const uint4*)(bp + i * b_step);
; #pragma unroll
;   for (int i = 0; i < 4; ++i) *(uint4*)(sA + (srow + i * 64) * LDT + sch) = ra[i];
; #pragma unroll
;   for (int i = 0; i < 2; ++i) *(uint4*)(sB + (srow + i * 64) * LDT + sch) = rb[i];
;   __syncthreads();
;   for (int kt = 0; kt < nk; ++kt) {
;     const int buf = kt & 1;
;     if (kt + 1 < nk) {
; #pragma unroll
;       for (int i = 0; i < 4; ++i) ra[i] = *(const uint4*)(ap + i * a_step + (kt + 1) * 64);
; #pragma unroll
;       for (int i = 0; i < 2; ++i) rb[i] = *(const uint4*)(bp + i * b_step + (kt + 1) * 64);
;     }
;     const bf16_t* cA = sA + buf * 256 * LDT + (wm * 64 + fr) * LDT + fq * 8;
;     const bf16_t* cB = sB + buf * 128 * LDT + (wn * 64 + fr) * LDT + fq * 8;
; #pragma unroll
;     for (int ks = 0; ks < 2; ++ks) {
;       bf16x8 af[4], bfg[4];
; #pragma unroll
;       for (int mi = 0; mi < 4; ++mi) af[mi] = *(const bf16x8*)(cA + mi * 16 * LDT + ks * 32);
; #pragma unroll
;       for (int ni = 0; ni < 4; ++ni) bfg[ni] = *(const bf16x8*)(cB + ni * 16 * LDT + ks * 32);
; #pragma unroll
;       for (int mi = 0; mi < 4; ++mi)
; #pragma unroll
;         for (int ni = 0; ni < 4; ++ni) acc[mi][ni] = MFMA16(af[mi], bfg[ni], acc[mi][ni]);
;     }
;     if (kt + 1 < nk) {
;       bf16_t* dA = sA + (buf ^ 1) * 256 * LDT;
;       bf16_t* dB = sB + (buf ^ 1) * 128 * LDT;
; #pragma unroll
;       for (int i = 0; i < 4; ++i) *(uint4*)(dA + (srow + i * 64) * LDT + sch) = ra[i];
; #pragma unroll
;       for (int i = 0; i < 2; ++i) *(uint4*)(dB + (srow + i * 64) * LDT + sch) = rb[i];
;     }
;     __syncthreads();
;   }
.LBB0_150:
	s_add_i32 s4, s7, s8
	s_cmpk_lt_i32 s4, 0x420
	s_mov_b64 s[2:3], -1
	s_cbranch_scc0 .LBB0_282
	s_ashr_i32 s2, s4, 31
	s_lshr_b32 s2, s2, 26
	s_add_i32 s2, s4, s2
	s_ashr_i32 s3, s2, 6
	s_lshl_b32 s5, s3, 2
	s_sub_i32 s5, 0x42, s5
	s_min_u32 s5, s5, 4
	v_cvt_f32_ubyte0_e32 v0, s5
	v_rcp_iflag_f32_e32 v0, v0
	s_andn2_b32 s2, s2, 63
	s_sub_i32 s9, s4, s2
	s_ashr_i32 s9, s9, 31
	v_mul_f32_e32 v0, 0x4f7ffffe, v0
	v_cvt_u32_f32_e32 v0, v0
	s_sub_i32 s10, 0, s5
	s_sub_i32 s2, s9, s2
	s_add_i32 s2, s4, s2
	v_readfirstlane_b32 s11, v0
	s_mul_i32 s10, s10, s11
	s_mul_hi_u32 s10, s11, s10
	s_xor_b32 s2, s2, s9
	s_add_i32 s11, s11, s10
	s_mul_hi_u32 s10, s2, s11
	s_mul_i32 s11, s10, s5
	s_sub_i32 s2, s2, s11
	s_add_i32 s11, s10, 1
	s_sub_i32 s12, s2, s5
	s_cmp_ge_u32 s2, s5
	s_cselect_b32 s10, s11, s10
	s_cselect_b32 s2, s12, s2
	s_add_i32 s11, s10, 1
	s_cmp_ge_u32 s2, s5
	s_cselect_b32 s2, s11, s10
	s_xor_b32 s2, s2, s9
	s_sub_i32 s9, s2, s9
	s_mul_i32 s2, s5, s9
	s_mul_i32 s3, s3, 60
	s_add_i32 s2, s2, s3
	s_sub_i32 s3, s4, s2
	s_lshl_b32 s2, s9, 6
	s_and_b32 s4, s2, 0xffffff80
	s_ashr_i32 s5, s4, 31
	s_lshl_b64 s[4:5], s[4:5], 1
	s_add_u32 s10, s40, s4
	v_mov_b32_e32 v65, v164
	s_addc_u32 s11, s41, s5
	s_lshl_b32 s4, s3, 8
	s_movk_i32 s5, 0x90
	v_ashrrev_i32_e32 v4, 3, v65
	v_add_u32_e32 v0, s4, v4
	v_ashrrev_i32_e32 v1, 31, v0
	v_lshlrev_b64 v[0:1], 11, v[0:1]
	v_lshlrev_b32_e32 v2, 4, v65
	v_lshl_add_u64 v[0:1], s[10:11], 0, v[0:1]
	v_and_b32_e32 v166, 0x70, v2
	v_lshl_add_u64 v[2:3], v[0:1], 0, v[166:167]
	v_lshl_add_u32 v0, s9, 7, v4
	v_mul_lo_u32 v112, v4, s5
	v_add3_u32 v113, 0, v166, v112
	s_mov_b32 s3, 0x20000
	v_ashrrev_i32_e32 v1, 31, v0
	v_lshlrev_b64 v[0:1], 8, v[0:1]
	v_lshl_add_u64 v[0:1], s[44:45], 0, v[0:1]
	v_lshl_add_u64 v[0:1], v[0:1], 0, v[166:167]
	v_add_co_u32_e32 v4, vcc, s3, v2
	s_mov_b32 s3, 0x40000
	s_nop 0
	v_addc_co_u32_e32 v5, vcc, 0, v3, vcc
	v_add_co_u32_e32 v6, vcc, s3, v2
	s_mov_b32 s3, 0x60000
	s_nop 0
	v_addc_co_u32_e32 v7, vcc, 0, v3, vcc
	v_add_co_u32_e32 v8, vcc, s3, v2
	s_movk_i32 s3, 0x4000
	s_nop 0
	v_addc_co_u32_e32 v9, vcc, 0, v3, vcc
	v_add_co_u32_e32 v10, vcc, s3, v0
	v_readlane_b32 s3, v255, 30
	s_nop 0
	v_addc_co_u32_e32 v11, vcc, 0, v1, vcc
	v_readlane_b32 s9, v255, 29
	v_bfe_u32 v66, v65, 4, 2
	v_ashrrev_i32_e32 v64, 8, v65
	v_add3_u32 v16, s9, v166, v112
	v_and_b32_e32 v67, 15, v65
	s_waitcnt vmcnt(12)
	ds_write_b128 v113, v[120:123]
	ds_write_b128 v16, v[136:139]
	ds_write_b128 v113, v[124:127] offset:9216
	ds_write_b128 v113, v[128:131] offset:18432
	ds_write_b128 v113, v[132:135] offset:27648
	ds_write_b128 v16, v[140:143] offset:9216
	v_and_b32_e32 v12, 0xcf, v65
	v_mul_u32_u24_e32 v12, 0x90, v12
	v_lshlrev_b32_e32 v13, 4, v66
	v_add3_u32 v114, 0, v12, v13
	v_lshl_or_b32 v12, v64, 6, v67
	v_mul_lo_u32 v12, v12, s5
	s_waitcnt lgkmcnt(0)
	s_barrier
	v_add3_u32 v116, s9, v12, v13
	ds_read_b128 v[12:15], v114
	ds_read_b128 v[16:19], v114 offset:2304
	ds_read_b128 v[20:23], v114 offset:4608
	ds_read_b128 v[24:27], v114 offset:6912
	ds_read_b128 v[28:31], v116
	ds_read_b128 v[32:35], v116 offset:2304
	ds_read_b128 v[36:39], v116 offset:4608
	ds_read_b128 v[40:43], v116 offset:6912
	s_waitcnt lgkmcnt(3)
	v_mfma_f32_16x16x32_bf16 v[44:47], v[12:15], v[28:31], 0
	v_or_b32_e32 v67, s2, v67
	v_lshl_add_u32 v64, v64, 5, v67
	s_mov_b32 s9, 0xbe99999a
	s_waitcnt lgkmcnt(2)
	v_mfma_f32_16x16x32_bf16 v[48:51], v[12:15], v[32:35], 0
	s_waitcnt lgkmcnt(1)
	v_mfma_f32_16x16x32_bf16 v[52:55], v[12:15], v[36:39], 0
	s_waitcnt lgkmcnt(0)
	v_mfma_f32_16x16x32_bf16 v[12:15], v[12:15], v[40:43], 0
	v_mfma_f32_16x16x32_bf16 v[56:59], v[16:19], v[28:31], 0
	v_mfma_f32_16x16x32_bf16 v[60:63], v[16:19], v[32:35], 0
	v_mfma_f32_16x16x32_bf16 v[68:71], v[16:19], v[36:39], 0
	v_mfma_f32_16x16x32_bf16 v[16:19], v[16:19], v[40:43], 0
	v_mfma_f32_16x16x32_bf16 v[72:75], v[20:23], v[28:31], 0
	v_mfma_f32_16x16x32_bf16 v[76:79], v[20:23], v[32:35], 0
	v_mfma_f32_16x16x32_bf16 v[80:83], v[20:23], v[36:39], 0
	v_mfma_f32_16x16x32_bf16 v[20:23], v[20:23], v[40:43], 0
	v_mfma_f32_16x16x32_bf16 v[28:31], v[24:27], v[28:31], 0
	v_mfma_f32_16x16x32_bf16 v[32:35], v[24:27], v[32:35], 0
	v_mfma_f32_16x16x32_bf16 v[36:39], v[24:27], v[36:39], 0
	v_mfma_f32_16x16x32_bf16 v[24:27], v[24:27], v[40:43], 0
	ds_read_b128 v[40:43], v114 offset:64
	ds_read_b128 v[84:87], v114 offset:2368
	ds_read_b128 v[88:91], v114 offset:4672
	ds_read_b128 v[92:95], v114 offset:6976
	ds_read_b128 v[96:99], v116 offset:64
	ds_read_b128 v[100:103], v116 offset:2368
	ds_read_b128 v[104:107], v116 offset:4672
	ds_read_b128 v[108:111], v116 offset:6976
	s_waitcnt lgkmcnt(3)
	v_mfma_f32_16x16x32_bf16 v[44:47], v[40:43], v[96:99], v[44:47]
	s_waitcnt lgkmcnt(2)
	v_mfma_f32_16x16x32_bf16 v[48:51], v[40:43], v[100:103], v[48:51]
	s_waitcnt lgkmcnt(1)
	v_mfma_f32_16x16x32_bf16 v[52:55], v[40:43], v[104:107], v[52:55]
	s_waitcnt lgkmcnt(0)
	v_mfma_f32_16x16x32_bf16 v[12:15], v[40:43], v[108:111], v[12:15]
	v_mfma_f32_16x16x32_bf16 v[40:43], v[84:87], v[96:99], v[56:59]
	v_mfma_f32_16x16x32_bf16 v[56:59], v[84:87], v[100:103], v[60:63]
	v_mfma_f32_16x16x32_bf16 v[60:63], v[84:87], v[104:107], v[68:71]
	v_mfma_f32_16x16x32_bf16 v[68:71], v[88:91], v[96:99], v[72:75]
	v_mfma_f32_16x16x32_bf16 v[72:75], v[88:91], v[100:103], v[76:79]
	v_mfma_f32_16x16x32_bf16 v[76:79], v[88:91], v[104:107], v[80:83]
	v_mfma_f32_16x16x32_bf16 v[16:19], v[84:87], v[108:111], v[16:19]
	v_add3_u32 v4, s3, v166, v112
	ds_write_b128 v113, v[144:147] offset:36864
	v_mfma_f32_16x16x32_bf16 v[20:23], v[88:91], v[108:111], v[20:23]
	ds_write_b128 v4, v[148:151]
	ds_write_b128 v113, v[152:155] offset:46080
	v_mfma_f32_16x16x32_bf16 v[28:31], v[92:95], v[96:99], v[28:31]
	ds_write_b128 v113, v[156:159] offset:55296
	v_mfma_f32_16x16x32_bf16 v[32:35], v[92:95], v[100:103], v[32:35]
	ds_write_b128 v113, v[160:163] offset:64512
	v_mfma_f32_16x16x32_bf16 v[36:39], v[92:95], v[104:107], v[36:39]
	ds_write_b128 v4, v[172:175] offset:9216
	v_mfma_f32_16x16x32_bf16 v[24:27], v[92:95], v[108:111], v[24:27]
	s_waitcnt lgkmcnt(0)
	s_barrier
; #define MFMA16(a, b, c) __builtin_amdgcn_mfma_f32_16x16x32_bf16(a, b, c, 0, 0, 0)
; template <int EPI>
; __device__ __forceinline__ void gemm_tile(const Params& p, const EpiArgs& ea, const bf16_t* __restrict__ A, int lda,
;                                           const bf16_t* __restrict__ Bt, int K, int m0, int n0, char* smem) {
;     ...
;   for (int kt = 0; kt < nk; ++kt) {
;     const int buf = kt & 1;
;     if (kt + 1 < nk) {
; #pragma unroll
;       for (int i = 0; i < 4; ++i) ra[i] = *(const uint4*)(ap + i * a_step + (kt + 1) * 64);
; #pragma unroll
;       for (int i = 0; i < 2; ++i) rb[i] = *(const uint4*)(bp + i * b_step + (kt + 1) * 64);
;     }
;     const bf16_t* cA = sA + buf * 256 * LDT + (wm * 64 + fr) * LDT + fq * 8;
;     const bf16_t* cB = sB + buf * 128 * LDT + (wn * 64 + fr) * LDT + fq * 8;
; #pragma unroll
;     for (int ks = 0; ks < 2; ++ks) {
;       bf16x8 af[4], bfg[4];
; #pragma unroll
;       for (int mi = 0; mi < 4; ++mi) af[mi] = *(const bf16x8*)(cA + mi * 16 * LDT + ks * 32);
; #pragma unroll
;       for (int ni = 0; ni < 4; ++ni) bfg[ni] = *(const bf16x8*)(cB + ni * 16 * LDT + ks * 32);
; #pragma unroll
;       for (int mi = 0; mi < 4; ++mi)
; #pragma unroll
;         for (int ni = 0; ni < 4; ++ni) acc[mi][ni] = MFMA16(af[mi], bfg[ni], acc[mi][ni]);
;     }
;     if (kt + 1 < nk) {
;       bf16_t* dA = sA + (buf ^ 1) * 256 * LDT;
;       bf16_t* dB = sB + (buf ^ 1) * 128 * LDT;
; #pragma unroll
;       for (int i = 0; i < 4; ++i) *(uint4*)(dA + (srow + i * 64) * LDT + sch) = ra[i];
; #pragma unroll
;       for (int i = 0; i < 2; ++i) *(uint4*)(dB + (srow + i * 64) * LDT + sch) = rb[i];
;     }
;     __syncthreads();
;   }
;     ...
;     } else if (EPI == EPI_LRU) {
; #pragma unroll
;       for (int nh = 0; nh < 2; ++nh) {
;         int ch = (n0 >> 1) + wn * 32 + nh * 16 + fr;
;         float ba = p.lru_b_a[ea.dir * 1024 + ch], bx = p.lru_b_x[ea.dir * 1024 + ch];
;         float sp8 = -8.0f * log1pf(__expf(-p.lru_lam[ea.dir * 1024 + ch]));
	v_readlane_b32 s60, v255, 24
	s_add_i32 s60, s60, s8
	s_add_i32 s60, s60, s7
	s_cmpk_lt_u32 s60, 0x420
	s_cbranch_scc0 .Llru_pf_skip1
	s_lshr_b32 s61, s60, 6
	s_and_b32 s62, s60, 63
	s_cmp_lt_u32 s61, 16
	s_cselect_b32 s63, 2, 1
	s_lshr_b32 s64, s62, s63
	s_lshl_b32 s65, s64, s63
	s_sub_i32 s65, s62, s65
	s_lshl_b32 s66, s61, 2
	s_add_i32 s65, s65, s66
	s_lshl_b32 s66, s64, 6
	s_and_b32 s66, s66, 0xffffff80
	s_lshl_b32 s66, s66, 1
	s_add_u32 s66, s40, s66
	s_addc_u32 s67, s41, 0
	s_lshl_b32 s65, s65, 8
	v_ashrrev_i32_e32 v184, 3, v164
	v_add_u32_e32 v180, s65, v184
	v_ashrrev_i32_e32 v181, 31, v180
	v_lshlrev_b64 v[180:181], 11, v[180:181]
	v_lshl_add_u64 v[180:181], s[66:67], 0, v[180:181]
	v_lshlrev_b32_e32 v182, 4, v164
	v_and_b32_e32 v182, 0x70, v182
	v_mov_b32_e32 v183, 0
	v_lshl_add_u64 v[180:181], v[180:181], 0, v[182:183]
	v_lshl_add_u32 v186, s64, 7, v184
	v_ashrrev_i32_e32 v187, 31, v186
	v_lshlrev_b64 v[186:187], 8, v[186:187]
	v_lshl_add_u64 v[186:187], s[44:45], 0, v[186:187]
	v_lshl_add_u64 v[186:187], v[186:187], 0, v[182:183]
	global_load_dwordx4 v[120:123], v[180:181], off
	global_load_dwordx4 v[144:147], v[180:181], off offset:128
	global_load_dwordx4 v[136:139], v[186:187], off
	global_load_dwordx4 v[148:151], v[186:187], off offset:128
	s_mov_b64 s[62:63], 0x20000
	v_lshl_add_u64 v[190:191], v[180:181], 0, s[62:63]
	global_load_dwordx4 v[124:127], v[190:191], off
	global_load_dwordx4 v[152:155], v[190:191], off offset:128
	v_lshl_add_u64 v[190:191], v[190:191], 0, s[62:63]
	global_load_dwordx4 v[128:131], v[190:191], off
	global_load_dwordx4 v[156:159], v[190:191], off offset:128
	v_lshl_add_u64 v[190:191], v[190:191], 0, s[62:63]
	global_load_dwordx4 v[132:135], v[190:191], off
	global_load_dwordx4 v[160:163], v[190:191], off offset:128
	s_mov_b64 s[62:63], 0x4000
	v_lshl_add_u64 v[190:191], v[186:187], 0, s[62:63]
	global_load_dwordx4 v[140:143], v[190:191], off
	global_load_dwordx4 v[172:175], v[190:191], off offset:128
.Llru_pf_skip1:
	ds_read_b128 v[0:3], v114 offset:36864
	ds_read_b128 v[4:7], v114 offset:39168
	ds_read_b128 v[8:11], v114 offset:41472
	ds_read_b128 v[80:83], v114 offset:43776
	ds_read_b128 v[84:87], v116 offset:18432
	ds_read_b128 v[88:91], v116 offset:20736
	ds_read_b128 v[92:95], v116 offset:23040
	ds_read_b128 v[96:99], v116 offset:25344
	s_waitcnt lgkmcnt(3)
	v_mfma_f32_16x16x32_bf16 v[44:47], v[0:3], v[84:87], v[44:47]
	s_waitcnt lgkmcnt(2)
	v_mfma_f32_16x16x32_bf16 v[48:51], v[0:3], v[88:91], v[48:51]
	s_waitcnt lgkmcnt(1)
	v_mfma_f32_16x16x32_bf16 v[52:55], v[0:3], v[92:95], v[52:55]
	s_waitcnt lgkmcnt(0)
	v_mfma_f32_16x16x32_bf16 v[0:3], v[0:3], v[96:99], v[12:15]
	v_mfma_f32_16x16x32_bf16 v[12:15], v[4:7], v[84:87], v[40:43]
	v_mfma_f32_16x16x32_bf16 v[40:43], v[4:7], v[88:91], v[56:59]
	v_mfma_f32_16x16x32_bf16 v[100:103], v[4:7], v[92:95], v[60:63]
	v_mfma_f32_16x16x32_bf16 v[4:7], v[4:7], v[96:99], v[16:19]
	v_mfma_f32_16x16x32_bf16 v[16:19], v[8:11], v[84:87], v[68:71]
	v_mfma_f32_16x16x32_bf16 v[68:71], v[8:11], v[88:91], v[72:75]
	v_mfma_f32_16x16x32_bf16 v[72:75], v[8:11], v[92:95], v[76:79]
	v_mfma_f32_16x16x32_bf16 v[8:11], v[8:11], v[96:99], v[20:23]
	v_mfma_f32_16x16x32_bf16 v[76:79], v[80:83], v[84:87], v[28:31]
	v_mfma_f32_16x16x32_bf16 v[84:87], v[80:83], v[88:91], v[32:35]
	v_mfma_f32_16x16x32_bf16 v[88:91], v[80:83], v[92:95], v[36:39]
	v_mfma_f32_16x16x32_bf16 v[80:83], v[80:83], v[96:99], v[24:27]
	ds_read_b128 v[20:23], v114 offset:36928
	s_nop 1
	ds_read_b128 v[24:27], v114 offset:39232
	ds_read_b128 v[92:95], v114 offset:41536
	ds_read_b128 v[96:99], v114 offset:43840
	ds_read_b128 v[104:107], v116 offset:18496
	ds_read_b128 v[108:111], v116 offset:20800
	ds_read_b128 v[112:115], v116 offset:23104
	ds_read_b128 v[116:119], v116 offset:25408
	s_waitcnt lgkmcnt(0)
	s_barrier
	s_load_dwordx2 s[2:3], s[0:1], 0xc0
	s_load_dwordx4 s[12:15], s[0:1], 0xd0
	v_mfma_f32_16x16x32_bf16 v[60:63], v[20:23], v[104:107], v[44:47]
	v_mfma_f32_16x16x32_bf16 v[44:47], v[24:27], v[104:107], v[12:15]
	v_mfma_f32_16x16x32_bf16 v[40:43], v[24:27], v[108:111], v[40:43]
	v_mfma_f32_16x16x32_bf16 v[36:39], v[24:27], v[112:115], v[100:103]
	v_mfma_f32_16x16x32_bf16 v[32:35], v[24:27], v[116:119], v[4:7]
	v_mfma_f32_16x16x32_bf16 v[24:27], v[92:95], v[108:111], v[68:71]
	s_nop 2
	v_add_u32_e32 v68, s6, v64
	v_ashrrev_i32_e32 v69, 31, v68
	v_lshlrev_b64 v[68:69], 2, v[68:69]
	v_mfma_f32_16x16x32_bf16 v[56:59], v[20:23], v[108:111], v[48:51]
	v_mfma_f32_16x16x32_bf16 v[52:55], v[20:23], v[112:115], v[52:55]
	v_mfma_f32_16x16x32_bf16 v[48:51], v[20:23], v[116:119], v[0:3]
	v_mfma_f32_16x16x32_bf16 v[20:23], v[92:95], v[112:115], v[72:75]
	s_waitcnt lgkmcnt(0)
	s_nop 1
	v_lshl_add_u64 v[72:73], s[14:15], 0, v[68:69]
	global_load_dword v67, v[72:73], off
	v_lshl_add_u64 v[74:75], s[2:3], 0, v[68:69]
	v_mfma_f32_16x16x32_bf16 v[0:3], v[96:99], v[116:119], v[80:83]
	s_mov_b32 s2, 0x3f2aaaab
	s_waitcnt vmcnt(0)
	v_mul_f32_e32 v67, 0xbfb8aa3b, v67
	global_load_dword v83, v[74:75], off
	v_exp_f32_e32 v67, v67
	v_mfma_f32_16x16x32_bf16 v[12:15], v[96:99], v[104:107], v[76:79]
	v_add_f32_e32 v70, 1.0, v67
	s_nop 1
	v_lshl_add_u64 v[76:77], s[12:13], 0, v[68:69]
	v_add_f32_e32 v68, -1.0, v70
	global_load_dword v82, v[76:77], off
	v_sub_f32_e32 v69, v68, v70
	v_add_f32_e32 v69, 1.0, v69
	v_sub_f32_e32 v68, v67, v68
	v_add_f32_e32 v71, v68, v69
	v_frexp_mant_f32_e32 v68, v70
	v_cmp_gt_f32_e32 vcc, s2, v68
	v_cvt_f64_f32_e32 v[68:69], v70
	v_frexp_exp_i32_f64_e32 v68, v[68:69]
	v_mfma_f32_16x16x32_bf16 v[28:31], v[92:95], v[104:107], v[16:19]
	s_mov_b32 s2, 0x3f317218
	s_waitcnt vmcnt(1)
;   __host__ __device__ __forceinline__ bf16_t* XC() const { return (bf16_t*)(wsl() + OFF_FFN); }
; __device__ __forceinline__ float bf2f(bf16_t h) { return __uint_as_float(((uint32_t)h) << 16); }
; __device__ __forceinline__ uint32_t pack2(float a, float b) { uint32_t r; asm("v_cvt_pk_bf16_f32 %0, %1, %2" : "=v"(r) : "v"(a), "v"(b)); return r; }
; __device__ __forceinline__ float sigmoidf_(float x) { return __builtin_amdgcn_rcpf(1.0f + __expf(-x)); }
; template <int EPI>
; __device__ __forceinline__ void gemm_tile(const Params& p, const EpiArgs& ea, const bf16_t* __restrict__ A, int lda,
;                                           const bf16_t* __restrict__ Bt, int K, int m0, int n0, char* smem) {
;     ...
;       for (int nh = 0; nh < 2; ++nh) {
;         int ch = (n0 >> 1) + wn * 32 + nh * 16 + fr;
;         float ba = p.lru_b_a[ea.dir * 1024 + ch], bx = p.lru_b_x[ea.dir * 1024 + ch];
;         float sp8 = -8.0f * log1pf(__expf(-p.lru_lam[ea.dir * 1024 + ch]));
; #pragma unroll
;         for (int j = 0; j < 4; ++j) {
;           float r = sigmoidf_(acc[mi][nh * 2][j] + ba);
;           float ig = sigmoidf_(acc[mi][nh * 2 + 1][j] + bx);
;           float la = r * sp8;
;           float x2 = 2.0f * la;
;           float poly = -x2 * (1.0f + x2 * (0.5f + x2 * (0.16666667f + x2 * (0.041666668f + x2 * (0.008333334f + x2 * 0.0013888889f)))));
;           float em = (x2 < -0.3f) ? (1.0f - __expf(x2)) : poly;
;           float u = bf2f(p.XC()[(size_t)(r0 + j) * D + ch]);
;           float inp = __builtin_amdgcn_sqrtf(fmaxf(em, 0.0f)) * (ig * u);
;           ea.outu[(size_t)(r0 + j) * D + ch] = pack2(la, inp);
	v_add_f32_e32 v60, v60, v83
	v_mfma_f32_16x16x32_bf16 v[16:19], v[92:95], v[116:119], v[8:11]
	v_mul_f32_e32 v60, 0xbfb8aa3b, v60
	v_exp_f32_e32 v60, v60
	v_mfma_f32_16x16x32_bf16 v[8:11], v[96:99], v[108:111], v[84:87]
	v_add_f32_e32 v60, 1.0, v60
	v_rcp_f32_e32 v60, v60
	s_nop 0
	v_subbrev_co_u32_e32 v84, vcc, 0, v68, vcc
	v_sub_u32_e32 v68, 0, v84
	v_ldexp_f32 v69, v70, v68
	v_add_f32_e32 v70, -1.0, v69
	v_add_f32_e32 v78, 1.0, v69
	v_ldexp_f32 v68, v71, v68
	v_add_f32_e32 v71, 1.0, v70
	v_add_f32_e32 v79, -1.0, v78
	v_sub_f32_e32 v71, v69, v71
	v_sub_f32_e32 v69, v69, v79
	v_add_f32_e32 v71, v68, v71
	v_add_f32_e32 v68, v68, v69
	v_add_f32_e32 v85, v78, v68
	v_rcp_f32_e32 v87, v85
	v_sub_f32_e32 v69, v85, v78
	v_sub_f32_e32 v86, v68, v69
	v_add_f32_e32 v69, v70, v71
	v_mfma_f32_16x16x32_bf16 v[4:7], v[96:99], v[112:115], v[88:91]
	v_sub_f32_e32 v68, v69, v70
	s_nop 1
	v_mul_f32_e32 v89, v69, v87
	v_mul_f32_e32 v70, v85, v89
	v_fma_f32 v78, v89, v85, -v70
	v_fmac_f32_e32 v78, v89, v86
	v_sub_f32_e32 v88, v71, v68
	v_add_f32_e32 v68, v70, v78
	v_sub_f32_e32 v71, v69, v68
	v_pk_add_f32 v[80:81], v[68:69], v[70:71] neg_lo:[0,1] neg_hi:[0,1]
	v_mov_b32_e32 v79, v68
	v_pk_add_f32 v[68:69], v[80:81], v[78:79] neg_lo:[0,1] neg_hi:[0,1]
	s_nop 0
	v_add_f32_e32 v69, v88, v69
	v_add_f32_e32 v68, v68, v69
	v_add_f32_e32 v69, v71, v68
	v_mul_f32_e32 v88, v87, v69
	v_mul_f32_e32 v70, v85, v88
	v_fma_f32 v78, v88, v85, -v70
	v_fmac_f32_e32 v78, v88, v86
	v_sub_f32_e32 v71, v71, v69
	v_add_f32_e32 v85, v68, v71
	v_add_f32_e32 v68, v70, v78
	v_sub_f32_e32 v71, v69, v68
	v_pk_add_f32 v[80:81], v[68:69], v[70:71] neg_lo:[0,1] neg_hi:[0,1]
	v_mov_b32_e32 v79, v68
	v_pk_add_f32 v[68:69], v[80:81], v[78:79] neg_lo:[0,1] neg_hi:[0,1]
	s_nop 0
	v_add_f32_e32 v69, v85, v69
	v_add_f32_e32 v68, v68, v69
	v_add_f32_e32 v69, v89, v88
	v_add_f32_e32 v68, v71, v68
	v_sub_f32_e32 v70, v69, v89
	v_mul_f32_e32 v68, v87, v68
	v_sub_f32_e32 v70, v88, v70
	v_add_f32_e32 v70, v70, v68
	v_add_f32_e32 v78, v69, v70
	v_mul_f32_e32 v79, v78, v78
	v_fmamk_f32 v68, v79, 0x3e9b6dac, v165
	v_fmaak_f32 v171, v79, v68, 0x3f2aaada
	v_cvt_f32_i32_e32 v68, v84
	v_sub_f32_e32 v69, v78, v69
	v_sub_f32_e32 v69, v70, v69
	v_ldexp_f32 v80, v69, 1
	v_mul_f32_e32 v69, v78, v79
	v_ldexp_f32 v71, v78, 1
	v_pk_mul_f32 v[78:79], v[68:69], v[170:171]
	s_nop 0
	v_fma_f32 v70, v68, s2, -v78
	v_fmac_f32_e32 v70, 0xb102e308, v68
	v_pk_add_f32 v[68:69], v[78:79], v[70:71]
	s_mov_b32 s2, 0x7f800000
	v_sub_f32_e32 v71, v69, v71
	v_sub_f32_e32 v71, v79, v71
	v_add_f32_e32 v81, v80, v71
	v_mov_b32_e32 v80, v78
	v_pk_add_f32 v[78:79], v[68:69], v[78:79] neg_lo:[0,1] neg_hi:[0,1]
	v_pk_add_f32 v[84:85], v[68:69], v[80:81]
	v_mov_b32_e32 v71, v68
	v_mov_b32_e32 v79, v85
	v_pk_add_f32 v[86:87], v[70:71], v[78:79] neg_lo:[0,1] neg_hi:[0,1]
	v_pk_add_f32 v[70:71], v[70:71], v[78:79]
	v_mov_b32_e32 v80, v81
	v_pk_add_f32 v[78:79], v[70:71], v[68:69] op_sel:[1,0] op_sel_hi:[0,1] neg_lo:[0,1] neg_hi:[0,1]
	v_pk_add_f32 v[88:89], v[84:85], v[78:79] op_sel_hi:[1,0] neg_lo:[0,1] neg_hi:[0,1]
	v_mov_b32_e32 v84, v85
	v_mov_b32_e32 v85, v71
	v_pk_mov_b32 v[78:79], v[68:69], v[78:79] op_sel:[1,0]
	v_mov_b32_e32 v81, v68
	v_pk_add_f32 v[78:79], v[84:85], v[78:79] neg_lo:[0,1] neg_hi:[0,1]
	v_mov_b32_e32 v88, v86
	v_pk_add_f32 v[68:69], v[80:81], v[78:79] neg_lo:[0,1] neg_hi:[0,1]
	v_mov_b32_e32 v87, v71
	v_pk_add_f32 v[78:79], v[88:89], v[68:69]
	v_cmp_neq_f32_e32 vcc, s2, v67
	v_pk_add_f32 v[80:81], v[78:79], v[78:79] op_sel:[0,1] op_sel_hi:[1,0]
	s_mov_b32 s2, 0x33800000
	v_pk_add_f32 v[70:71], v[70:71], v[80:81] op_sel:[1,0] op_sel_hi:[0,1]
	v_mov_b32_e32 v79, v70
	v_pk_add_f32 v[84:85], v[78:79], v[86:87] neg_lo:[0,1] neg_hi:[0,1]
	v_mov_b32_e32 v69, v80
	v_sub_f32_e32 v71, v78, v84
	v_pk_add_f32 v[68:69], v[68:69], v[84:85] neg_lo:[0,1] neg_hi:[0,1]
	v_sub_f32_e32 v71, v86, v71
	v_add_f32_e32 v68, v68, v71
	v_add_f32_e32 v68, v68, v69
	v_add_f32_e32 v68, v70, v68
	v_cndmask_b32_e32 v68, v225, v68, vcc
	v_cmp_ngt_f32_e32 vcc, -1.0, v67
	s_nop 1
	v_cndmask_b32_e32 v68, v226, v68, vcc
	v_cmp_neq_f32_e32 vcc, -1.0, v67
	s_nop 1
	v_cndmask_b32_e32 v68, v227, v68, vcc
	v_cmp_lt_f32_e64 vcc, |v67|, s2
	s_nop 1
	v_cndmask_b32_e32 v67, v68, v67, vcc
	v_mul_f32_e32 v84, 0xc1000000, v67
	v_mul_f32_e32 v60, v60, v84
	v_add_f32_e32 v67, v60, v60
	v_cmp_ngt_f32_e32 vcc, s9, v67
	s_and_saveexec_b64 s[2:3], vcc
	s_xor_b64 s[2:3], exec, s[2:3]
	v_fmamk_f32 v68, v67, 0x3ab60b61, v169
	v_fmaak_f32 v68, v67, v68, 0x3d2aaaab
	v_fmaak_f32 v68, v67, v68, 0x3e2aaaab
	v_fma_f32 v68, v67, v68, 0.5
	v_fma_f32 v68, v67, v68, 1.0
	v_mul_f32_e64 v78, v68, -v67
	s_andn2_saveexec_b64 s[2:3], s[2:3]
	v_mul_f32_e32 v67, 0x3fb8aa3b, v67
	v_exp_f32_e32 v67, v67
	s_nop 0
	v_sub_f32_e32 v78, 1.0, v67
	s_or_b64 exec, exec, s[2:3]
	v_and_b32_e32 v65, 0xc0, v65
	v_lshlrev_b32_e32 v66, 2, v66
	v_or3_b32 v66, v66, v65, s4
	v_and_b32_e32 v179, 0xff, v66
	v_mul_u32_u24_e32 v179, 0x90, v179
	v_and_b32_e32 v188, 63, v64
	v_lshl_add_u32 v179, v188, 1, v179
	v_bfe_u32 v188, v64, 6, 1
	v_mul_u32_u24_e32 v188, 0x9000, v188
	v_add_u32_e32 v178, v179, v188
	v_ashrrev_i32_e32 v67, 31, v66
	v_ashrrev_i32_e32 v65, 31, v64
	v_lshlrev_b64 v[68:69], 10, v[66:67]
	v_lshl_add_u64 v[80:81], v[68:69], 0, v[64:65]
	v_lshl_add_u64 v[70:71], v[80:81], 1, s[40:41]
	ds_read_u16 v67, v178 offset:0
	s_waitcnt vmcnt(0)
	v_add_f32_e32 v56, v56, v82
	v_mul_f32_e32 v56, 0xbfb8aa3b, v56
	v_exp_f32_e32 v56, v56
	v_max_f32_e32 v78, v78, v78
	v_max_f32_e32 v78, 0, v78
	v_sqrt_f32_e32 v78, v78
	v_add_f32_e32 v56, 1.0, v56
	v_rcp_f32_e32 v56, v56
	s_waitcnt lgkmcnt(0)
;   __host__ __device__ __forceinline__ bf16_t* XC() const { return (bf16_t*)(wsl() + OFF_FFN); }
; __device__ __forceinline__ float bf2f(bf16_t h) { return __uint_as_float(((uint32_t)h) << 16); }
; __device__ __forceinline__ uint32_t pack2(float a, float b) { uint32_t r; asm("v_cvt_pk_bf16_f32 %0, %1, %2" : "=v"(r) : "v"(a), "v"(b)); return r; }
; __device__ __forceinline__ float sigmoidf_(float x) { return __builtin_amdgcn_rcpf(1.0f + __expf(-x)); }
; template <int EPI>
; __device__ __forceinline__ void gemm_tile(const Params& p, const EpiArgs& ea, const bf16_t* __restrict__ A, int lda,
;                                           const bf16_t* __restrict__ Bt, int K, int m0, int n0, char* smem) {
;     ...
;         for (int j = 0; j < 4; ++j) {
;           float r = sigmoidf_(acc[mi][nh * 2][j] + ba);
;           float ig = sigmoidf_(acc[mi][nh * 2 + 1][j] + bx);
;           float la = r * sp8;
;           float x2 = 2.0f * la;
;           float poly = -x2 * (1.0f + x2 * (0.5f + x2 * (0.16666667f + x2 * (0.041666668f + x2 * (0.008333334f + x2 * 0.0013888889f)))));
;           float em = (x2 < -0.3f) ? (1.0f - __expf(x2)) : poly;
;           float u = bf2f(p.XC()[(size_t)(r0 + j) * D + ch]);
;           float inp = __builtin_amdgcn_sqrtf(fmaxf(em, 0.0f)) * (ig * u);
;           ea.outu[(size_t)(r0 + j) * D + ch] = pack2(la, inp);
;         }
	v_lshlrev_b32_e32 v67, 16, v67
	v_mul_f32_e32 v56, v56, v67
	v_mul_f32_e32 v56, v78, v56
	v_cvt_pk_bf16_f32 v56, v60, v56
	v_lshl_add_u64 v[78:79], v[80:81], 2, s[42:43]
	v_mov_b32_e32 v189, v56
	v_add_f32_e32 v56, v61, v83
	v_mul_f32_e32 v56, 0xbfb8aa3b, v56
	v_exp_f32_e32 v56, v56
	s_nop 0
	v_add_f32_e32 v56, 1.0, v56
	v_rcp_f32_e32 v56, v56
	s_nop 0
	v_mul_f32_e32 v67, v56, v84
	v_add_f32_e32 v56, v67, v67
	v_cmp_ngt_f32_e32 vcc, s9, v56
	s_and_saveexec_b64 s[2:3], vcc
	s_xor_b64 s[2:3], exec, s[2:3]
	v_fmamk_f32 v60, v56, 0x3ab60b61, v169
	v_fmaak_f32 v60, v56, v60, 0x3d2aaaab
	v_fmaak_f32 v60, v56, v60, 0x3e2aaaab
	v_fma_f32 v60, v56, v60, 0.5
	v_fma_f32 v60, v56, v60, 1.0
	v_mul_f32_e64 v78, v60, -v56
	s_andn2_saveexec_b64 s[2:3], s[2:3]
	v_mul_f32_e32 v56, 0x3fb8aa3b, v56
	v_exp_f32_e32 v56, v56
	s_nop 0
	v_sub_f32_e32 v78, 1.0, v56
	s_or_b64 exec, exec, s[2:3]
	v_add_f32_e32 v56, v57, v82
	v_mul_f32_e32 v56, 0xbfb8aa3b, v56
	v_exp_f32_e32 v56, v56
	v_add_f32_e32 v62, v62, v83
	v_mul_f32_e32 v62, 0xbfb8aa3b, v62
	v_exp_f32_e32 v62, v62
	v_add_f32_e32 v56, 1.0, v56
	v_rcp_f32_e32 v79, v56
	v_or_b32_e32 v56, 1, v66
	v_ashrrev_i32_e32 v57, 31, v56
	v_lshlrev_b64 v[56:57], 10, v[56:57]
	v_lshl_add_u64 v[80:81], v[56:57], 0, v[64:65]
	v_lshl_add_u64 v[60:61], v[80:81], 1, s[40:41]
	ds_read_u16 v85, v178 offset:144
	v_max_f32_e32 v78, v78, v78
	v_max_f32_e32 v78, 0, v78
	v_sqrt_f32_e32 v78, v78
	v_add_f32_e32 v62, 1.0, v62
	v_rcp_f32_e32 v62, v62
	s_waitcnt lgkmcnt(0)
	v_lshlrev_b32_e32 v85, 16, v85
	v_mul_f32_e32 v79, v79, v85
	v_mul_f32_e32 v78, v78, v79
	v_cvt_pk_bf16_f32 v67, v67, v78
	v_lshl_add_u64 v[78:79], v[80:81], 2, s[42:43]
	v_mul_f32_e32 v62, v62, v84
	v_mov_b32_e32 v190, v67
	v_add_f32_e32 v67, v62, v62
	v_cmp_ngt_f32_e32 vcc, s9, v67
	s_and_saveexec_b64 s[2:3], vcc
	s_xor_b64 s[2:3], exec, s[2:3]
	v_fmamk_f32 v78, v67, 0x3ab60b61, v169
	v_fmaak_f32 v78, v67, v78, 0x3d2aaaab
	v_fmaak_f32 v78, v67, v78, 0x3e2aaaab
	v_fma_f32 v78, v67, v78, 0.5
	v_fma_f32 v78, v67, v78, 1.0
	v_mul_f32_e64 v85, v78, -v67
	s_andn2_saveexec_b64 s[2:3], s[2:3]
	v_mul_f32_e32 v67, 0x3fb8aa3b, v67
	v_exp_f32_e32 v67, v67
	s_nop 0
	v_sub_f32_e32 v85, 1.0, v67
	s_or_b64 exec, exec, s[2:3]
	v_or_b32_e32 v78, 2, v66
	v_ashrrev_i32_e32 v79, 31, v78
	v_lshlrev_b64 v[78:79], 10, v[78:79]
	v_lshl_add_u64 v[86:87], v[78:79], 0, v[64:65]
	v_lshl_add_u64 v[80:81], v[86:87], 1, s[40:41]
	ds_read_u16 v88, v178 offset:288
	v_add_f32_e32 v63, v63, v83
	v_mul_f32_e32 v63, 0xbfb8aa3b, v63
	v_add_f32_e32 v58, v58, v82
	v_exp_f32_e32 v63, v63
	v_mul_f32_e32 v58, 0xbfb8aa3b, v58
	v_exp_f32_e32 v58, v58
	v_max_f32_e32 v67, v85, v85
	v_add_f32_e32 v63, 1.0, v63
	v_rcp_f32_e32 v63, v63
	v_add_f32_e32 v58, 1.0, v58
	v_max_f32_e32 v67, 0, v67
	v_rcp_f32_e32 v89, v58
	v_sqrt_f32_e32 v85, v67
	v_mul_f32_e32 v67, v63, v84
	v_add_f32_e32 v58, v67, v67
	v_lshl_add_u64 v[86:87], v[86:87], 2, s[42:43]
	v_cmp_ngt_f32_e32 vcc, s9, v58
	s_waitcnt lgkmcnt(0)
	v_lshlrev_b32_e32 v63, 16, v88
	v_mul_f32_e32 v63, v89, v63
	v_mul_f32_e32 v63, v85, v63
	v_cvt_pk_bf16_f32 v62, v62, v63
	v_mov_b32_e32 v191, v62
	s_and_saveexec_b64 s[2:3], vcc
	s_xor_b64 s[2:3], exec, s[2:3]
	v_fmamk_f32 v62, v58, 0x3ab60b61, v169
	v_fmaak_f32 v62, v58, v62, 0x3d2aaaab
	v_fmaak_f32 v62, v58, v62, 0x3e2aaaab
	v_fma_f32 v62, v58, v62, 0.5
	v_fma_f32 v62, v58, v62, 1.0
	v_mul_f32_e64 v85, v62, -v58
	s_andn2_saveexec_b64 s[2:3], s[2:3]
	v_mul_f32_e32 v58, 0x3fb8aa3b, v58
	v_exp_f32_e32 v58, v58
	s_nop 0
	v_sub_f32_e32 v85, 1.0, v58
	s_or_b64 exec, exec, s[2:3]
	v_add_f32_e32 v58, v59, v82
	v_mul_f32_e32 v58, 0xbfb8aa3b, v58
	v_exp_f32_e32 v58, v58
	v_max_f32_e32 v85, v85, v85
	v_max_f32_e32 v85, 0, v85
	v_sqrt_f32_e32 v85, v85
	v_add_f32_e32 v58, 1.0, v58
	v_rcp_f32_e32 v88, v58
	v_or_b32_e32 v58, 3, v66
	v_ashrrev_i32_e32 v59, 31, v58
	v_lshlrev_b64 v[58:59], 10, v[58:59]
	v_lshl_add_u64 v[86:87], v[58:59], 0, v[64:65]
	v_lshl_add_u64 v[62:63], v[86:87], 1, s[40:41]
	ds_read_u16 v89, v178 offset:432
	v_lshl_add_u64 v[86:87], v[86:87], 2, s[42:43]
	s_mov_b32 s2, 0x3f2aaaab
	s_waitcnt lgkmcnt(0)
	v_lshlrev_b32_e32 v89, 16, v89
	v_mul_f32_e32 v88, v88, v89
	v_mul_f32_e32 v85, v85, v88
	v_cvt_pk_bf16_f32 v67, v67, v85
	v_mov_b32_e32 v192, v67
	global_load_dword v74, v[74:75], off offset:64
	s_nop 0
	global_load_dword v67, v[76:77], off offset:64
	s_nop 0
	global_load_dword v72, v[72:73], off offset:64
	s_waitcnt vmcnt(2)
	v_add_f32_e32 v52, v52, v74
	v_mul_f32_e32 v52, 0xbfb8aa3b, v52
	s_waitcnt vmcnt(0)
;   __host__ __device__ __forceinline__ bf16_t* XC() const { return (bf16_t*)(wsl() + OFF_FFN); }
; __device__ __forceinline__ float bf2f(bf16_t h) { return __uint_as_float(((uint32_t)h) << 16); }
; __device__ __forceinline__ float sigmoidf_(float x) { return __builtin_amdgcn_rcpf(1.0f + __expf(-x)); }
; template <int EPI>
; __device__ __forceinline__ void gemm_tile(const Params& p, const EpiArgs& ea, const bf16_t* __restrict__ A, int lda,
;                                           const bf16_t* __restrict__ Bt, int K, int m0, int n0, char* smem) {
;     ...
;       for (int nh = 0; nh < 2; ++nh) {
;         int ch = (n0 >> 1) + wn * 32 + nh * 16 + fr;
;         float ba = p.lru_b_a[ea.dir * 1024 + ch], bx = p.lru_b_x[ea.dir * 1024 + ch];
;         float sp8 = -8.0f * log1pf(__expf(-p.lru_lam[ea.dir * 1024 + ch]));
; #pragma unroll
;         for (int j = 0; j < 4; ++j) {
;           float r = sigmoidf_(acc[mi][nh * 2][j] + ba);
;           float ig = sigmoidf_(acc[mi][nh * 2 + 1][j] + bx);
;           float la = r * sp8;
;           float x2 = 2.0f * la;
;           float poly = -x2 * (1.0f + x2 * (0.5f + x2 * (0.16666667f + x2 * (0.041666668f + x2 * (0.008333334f + x2 * 0.0013888889f)))));
;           float em = (x2 < -0.3f) ? (1.0f - __expf(x2)) : poly;
;           float u = bf2f(p.XC()[(size_t)(r0 + j) * D + ch]);
;           float inp = __builtin_amdgcn_sqrtf(fmaxf(em, 0.0f)) * (ig * u);
	v_mul_f32_e32 v72, 0xbfb8aa3b, v72
	v_exp_f32_e32 v75, v72
	v_exp_f32_e32 v52, v52
	v_add_f32_e32 v76, 1.0, v75
	v_add_f32_e32 v72, -1.0, v76
	v_sub_f32_e32 v73, v72, v76
	v_add_f32_e32 v73, 1.0, v73
	v_sub_f32_e32 v72, v75, v72
	v_add_f32_e32 v77, v72, v73
	v_frexp_mant_f32_e32 v72, v76
	v_cmp_gt_f32_e32 vcc, s2, v72
	v_cvt_f64_f32_e32 v[72:73], v76
	v_frexp_exp_i32_f64_e32 v72, v[72:73]
	v_subbrev_co_u32_e32 v85, vcc, 0, v72, vcc
	v_sub_u32_e32 v72, 0, v85
	v_ldexp_f32 v73, v76, v72
	v_add_f32_e32 v76, -1.0, v73
	v_add_f32_e32 v86, 1.0, v73
	v_ldexp_f32 v72, v77, v72
	v_add_f32_e32 v77, 1.0, v76
	v_add_f32_e32 v87, -1.0, v86
	v_sub_f32_e32 v77, v73, v77
	v_sub_f32_e32 v73, v73, v87
	v_add_f32_e32 v77, v72, v77
	v_add_f32_e32 v72, v72, v73
	v_add_f32_e32 v90, v86, v72
	v_rcp_f32_e32 v92, v90
	v_sub_f32_e32 v73, v90, v86
	v_sub_f32_e32 v91, v72, v73
	v_add_f32_e32 v73, v76, v77
	v_mul_f32_e32 v94, v73, v92
	v_sub_f32_e32 v72, v73, v76
	v_mul_f32_e32 v76, v90, v94
	v_fma_f32 v86, v94, v90, -v76
	v_fmac_f32_e32 v86, v94, v91
	v_sub_f32_e32 v93, v77, v72
	v_add_f32_e32 v72, v76, v86
	v_sub_f32_e32 v77, v73, v72
	v_pk_add_f32 v[88:89], v[72:73], v[76:77] neg_lo:[0,1] neg_hi:[0,1]
	v_mov_b32_e32 v87, v72
	v_pk_add_f32 v[72:73], v[88:89], v[86:87] neg_lo:[0,1] neg_hi:[0,1]
	s_mov_b32 s2, 0x3f317218
	v_add_f32_e32 v73, v93, v73
	v_add_f32_e32 v72, v72, v73
	v_add_f32_e32 v73, v77, v72
	v_mul_f32_e32 v93, v92, v73
	v_mul_f32_e32 v76, v90, v93
	v_fma_f32 v86, v93, v90, -v76
	v_fmac_f32_e32 v86, v93, v91
	v_sub_f32_e32 v77, v77, v73
	v_add_f32_e32 v90, v72, v77
	v_add_f32_e32 v72, v76, v86
	v_sub_f32_e32 v77, v73, v72
	v_pk_add_f32 v[88:89], v[72:73], v[76:77] neg_lo:[0,1] neg_hi:[0,1]
	v_mov_b32_e32 v87, v72
	v_pk_add_f32 v[72:73], v[88:89], v[86:87] neg_lo:[0,1] neg_hi:[0,1]
	v_add_f32_e32 v52, 1.0, v52
	v_add_f32_e32 v73, v90, v73
	v_add_f32_e32 v72, v72, v73
	v_add_f32_e32 v73, v94, v93
	v_add_f32_e32 v72, v77, v72
	v_sub_f32_e32 v76, v73, v94
	v_mul_f32_e32 v72, v92, v72
	v_sub_f32_e32 v76, v93, v76
	v_add_f32_e32 v76, v76, v72
	v_add_f32_e32 v86, v73, v76
	v_mul_f32_e32 v87, v86, v86
	v_fmamk_f32 v72, v87, 0x3e9b6dac, v165
	v_fmaak_f32 v171, v87, v72, 0x3f2aaada
	v_cvt_f32_i32_e32 v72, v85
	v_sub_f32_e32 v73, v86, v73
	v_sub_f32_e32 v73, v76, v73
	v_ldexp_f32 v85, v73, 1
	v_mul_f32_e32 v73, v86, v87
	v_ldexp_f32 v77, v86, 1
	v_pk_mul_f32 v[86:87], v[72:73], v[170:171]
	v_rcp_f32_e32 v52, v52
	v_fma_f32 v76, v72, s2, -v86
	v_fmac_f32_e32 v76, 0xb102e308, v72
	v_pk_add_f32 v[72:73], v[86:87], v[76:77]
	v_mov_b32_e32 v88, v86
	v_sub_f32_e32 v77, v73, v77
	v_sub_f32_e32 v77, v87, v77
	v_add_f32_e32 v89, v85, v77
	v_pk_add_f32 v[86:87], v[72:73], v[86:87] neg_lo:[0,1] neg_hi:[0,1]
	v_pk_add_f32 v[90:91], v[72:73], v[88:89]
	v_mov_b32_e32 v77, v72
	v_mov_b32_e32 v87, v91
	v_pk_add_f32 v[92:93], v[76:77], v[86:87] neg_lo:[0,1] neg_hi:[0,1]
	v_pk_add_f32 v[76:77], v[76:77], v[86:87]
	v_mov_b32_e32 v88, v89
	v_pk_add_f32 v[86:87], v[76:77], v[72:73] op_sel:[1,0] op_sel_hi:[0,1] neg_lo:[0,1] neg_hi:[0,1]
	v_pk_add_f32 v[94:95], v[90:91], v[86:87] op_sel_hi:[1,0] neg_lo:[0,1] neg_hi:[0,1]
	v_mov_b32_e32 v90, v91
	v_mov_b32_e32 v91, v77
	v_pk_mov_b32 v[86:87], v[72:73], v[86:87] op_sel:[1,0]
	v_mov_b32_e32 v89, v72
	v_pk_add_f32 v[86:87], v[90:91], v[86:87] neg_lo:[0,1] neg_hi:[0,1]
	v_mov_b32_e32 v94, v92
	v_pk_add_f32 v[72:73], v[88:89], v[86:87] neg_lo:[0,1] neg_hi:[0,1]
	v_mov_b32_e32 v93, v77
	v_pk_add_f32 v[86:87], v[94:95], v[72:73]
	s_mov_b32 s2, 0x7f800000
	v_pk_add_f32 v[88:89], v[86:87], v[86:87] op_sel:[0,1] op_sel_hi:[1,0]
	v_cmp_neq_f32_e32 vcc, s2, v75
	v_pk_add_f32 v[76:77], v[76:77], v[88:89] op_sel:[1,0] op_sel_hi:[0,1]
	v_mov_b32_e32 v87, v76
	v_pk_add_f32 v[90:91], v[86:87], v[92:93] neg_lo:[0,1] neg_hi:[0,1]
	v_mov_b32_e32 v73, v88
	v_sub_f32_e32 v77, v86, v90
	v_pk_add_f32 v[72:73], v[72:73], v[90:91] neg_lo:[0,1] neg_hi:[0,1]
	v_sub_f32_e32 v77, v92, v77
	v_add_f32_e32 v72, v72, v77
	v_add_f32_e32 v72, v72, v73
	v_add_f32_e32 v72, v76, v72
	v_cndmask_b32_e32 v72, v225, v72, vcc
	v_cmp_ngt_f32_e32 vcc, -1.0, v75
	s_mov_b32 s2, 0x33800000
	s_nop 0
	v_cndmask_b32_e32 v72, v226, v72, vcc
	v_cmp_neq_f32_e32 vcc, -1.0, v75
	s_nop 1
	v_cndmask_b32_e32 v72, v227, v72, vcc
	v_cmp_lt_f32_e64 vcc, |v75|, s2
	s_nop 1
	v_cndmask_b32_e32 v72, v72, v75, vcc
	v_mul_f32_e32 v72, 0xc1000000, v72
	v_mul_f32_e32 v73, v52, v72
	v_add_f32_e32 v52, v73, v73
	v_cmp_ngt_f32_e32 vcc, s9, v52
	s_and_saveexec_b64 s[2:3], vcc
	s_xor_b64 s[2:3], exec, s[2:3]
	v_fmamk_f32 v75, v52, 0x3ab60b61, v169
	v_fmaak_f32 v75, v52, v75, 0x3d2aaaab
	v_fmaak_f32 v75, v52, v75, 0x3e2aaaab
	v_fma_f32 v75, v52, v75, 0.5
	v_fma_f32 v75, v52, v75, 1.0
	v_mul_f32_e64 v75, v75, -v52
	s_andn2_saveexec_b64 s[2:3], s[2:3]
	v_mul_f32_e32 v52, 0x3fb8aa3b, v52
	v_exp_f32_e32 v52, v52
	s_nop 0
	v_sub_f32_e32 v75, 1.0, v52
	s_or_b64 exec, exec, s[2:3]
	ds_read_u16 v76, v178 offset:32
	v_add_f32_e32 v48, v48, v67
	v_add_f32_e32 v71, v53, v74
	v_mul_f32_e32 v48, 0xbfb8aa3b, v48
	v_mul_f32_e32 v71, 0xbfb8aa3b, v71
	v_exp_f32_e32 v71, v71
	v_exp_f32_e32 v48, v48
	v_or_b32_e32 v52, 16, v64
	v_max_f32_e32 v70, v75, v75
	v_ashrrev_i32_e32 v53, 31, v52
	v_max_f32_e32 v70, 0, v70
	v_lshl_add_u64 v[68:69], v[68:69], 0, v[52:53]
	v_sqrt_f32_e32 v75, v70
	v_add_f32_e32 v70, 1.0, v71
	v_add_f32_e32 v48, 1.0, v48
	v_rcp_f32_e32 v77, v70
	v_lshl_add_u64 v[70:71], v[68:69], 2, s[42:43]
	v_rcp_f32_e32 v68, v48
	v_mul_f32_e32 v48, v77, v72
	v_add_f32_e32 v69, v48, v48
	v_cmp_ngt_f32_e32 vcc, s9, v69
	s_waitcnt lgkmcnt(0)
;   __host__ __device__ __forceinline__ bf16_t* XC() const { return (bf16_t*)(wsl() + OFF_FFN); }
; __device__ __forceinline__ float bf2f(bf16_t h) { return __uint_as_float(((uint32_t)h) << 16); }
; __device__ __forceinline__ uint32_t pack2(float a, float b) { uint32_t r; asm("v_cvt_pk_bf16_f32 %0, %1, %2" : "=v"(r) : "v"(a), "v"(b)); return r; }
; __device__ __forceinline__ float sigmoidf_(float x) { return __builtin_amdgcn_rcpf(1.0f + __expf(-x)); }
; template <int EPI>
; __device__ __forceinline__ void gemm_tile(const Params& p, const EpiArgs& ea, const bf16_t* __restrict__ A, int lda,
;                                           const bf16_t* __restrict__ Bt, int K, int m0, int n0, char* smem) {
;     ...
;       for (int nh = 0; nh < 2; ++nh) {
;         int ch = (n0 >> 1) + wn * 32 + nh * 16 + fr;
;         float ba = p.lru_b_a[ea.dir * 1024 + ch], bx = p.lru_b_x[ea.dir * 1024 + ch];
;         float sp8 = -8.0f * log1pf(__expf(-p.lru_lam[ea.dir * 1024 + ch]));
; #pragma unroll
;         for (int j = 0; j < 4; ++j) {
;           float r = sigmoidf_(acc[mi][nh * 2][j] + ba);
;           float ig = sigmoidf_(acc[mi][nh * 2 + 1][j] + bx);
;           float la = r * sp8;
;           float x2 = 2.0f * la;
;           float poly = -x2 * (1.0f + x2 * (0.5f + x2 * (0.16666667f + x2 * (0.041666668f + x2 * (0.008333334f + x2 * 0.0013888889f)))));
;           float em = (x2 < -0.3f) ? (1.0f - __expf(x2)) : poly;
;           float u = bf2f(p.XC()[(size_t)(r0 + j) * D + ch]);
;           float inp = __builtin_amdgcn_sqrtf(fmaxf(em, 0.0f)) * (ig * u);
;           ea.outu[(size_t)(r0 + j) * D + ch] = pack2(la, inp);
;         }
;       }
	v_lshlrev_b32_e32 v76, 16, v76
	v_mul_f32_e32 v68, v68, v76
	v_mul_f32_e32 v68, v75, v68
	v_cvt_pk_bf16_f32 v68, v73, v68
	v_mov_b32_e32 v193, v68
	s_and_saveexec_b64 s[2:3], vcc
	s_xor_b64 s[2:3], exec, s[2:3]
	v_fmamk_f32 v68, v69, 0x3ab60b61, v169
	v_fmaak_f32 v68, v69, v68, 0x3d2aaaab
	v_fmaak_f32 v68, v69, v68, 0x3e2aaaab
	v_fma_f32 v68, v69, v68, 0.5
	v_fma_f32 v68, v69, v68, 1.0
	v_mul_f32_e64 v68, v68, -v69
	s_andn2_saveexec_b64 s[2:3], s[2:3]
	v_mul_f32_e32 v68, 0x3fb8aa3b, v69
	v_exp_f32_e32 v68, v68
	s_nop 0
	v_sub_f32_e32 v68, 1.0, v68
	s_or_b64 exec, exec, s[2:3]
	ds_read_u16 v60, v178 offset:176
	v_add_f32_e32 v54, v54, v74
	v_add_f32_e32 v49, v49, v67
	v_mul_f32_e32 v54, 0xbfb8aa3b, v54
	v_mul_f32_e32 v49, 0xbfb8aa3b, v49
	v_exp_f32_e32 v54, v54
	v_exp_f32_e32 v49, v49
	v_max_f32_e32 v61, v68, v68
	v_max_f32_e32 v61, 0, v61
	v_add_f32_e32 v54, 1.0, v54
	v_rcp_f32_e32 v54, v54
	v_add_f32_e32 v49, 1.0, v49
	v_rcp_f32_e32 v68, v49
	v_sqrt_f32_e32 v61, v61
	v_mul_f32_e32 v49, v54, v72
	v_lshl_add_u64 v[56:57], v[56:57], 0, v[52:53]
	v_add_f32_e32 v54, v49, v49
	v_lshl_add_u64 v[56:57], v[56:57], 2, s[42:43]
	v_cmp_ngt_f32_e32 vcc, s9, v54
	s_waitcnt lgkmcnt(0)
	v_lshlrev_b32_e32 v60, 16, v60
	v_mul_f32_e32 v60, v68, v60
	v_mul_f32_e32 v60, v61, v60
	v_cvt_pk_bf16_f32 v48, v48, v60
	v_mov_b32_e32 v194, v48
	s_and_saveexec_b64 s[2:3], vcc
	s_xor_b64 s[2:3], exec, s[2:3]
	v_fmamk_f32 v48, v54, 0x3ab60b61, v169
	v_fmaak_f32 v48, v54, v48, 0x3d2aaaab
	v_fmaak_f32 v48, v54, v48, 0x3e2aaaab
	v_fma_f32 v48, v54, v48, 0.5
	v_fma_f32 v48, v54, v48, 1.0
	v_mul_f32_e64 v48, v48, -v54
	s_andn2_saveexec_b64 s[2:3], s[2:3]
	v_mul_f32_e32 v48, 0x3fb8aa3b, v54
	v_exp_f32_e32 v48, v48
	s_nop 0
	v_sub_f32_e32 v48, 1.0, v48
	s_or_b64 exec, exec, s[2:3]
	ds_read_u16 v60, v178 offset:320
	v_add_f32_e32 v54, v55, v74
	v_add_f32_e32 v50, v50, v67
	v_mul_f32_e32 v54, 0xbfb8aa3b, v54
	v_mul_f32_e32 v50, 0xbfb8aa3b, v50
	v_exp_f32_e32 v61, v54
	v_exp_f32_e32 v50, v50
	v_lshl_add_u64 v[56:57], v[78:79], 0, v[52:53]
	v_max_f32_e32 v48, v48, v48
	v_max_f32_e32 v48, 0, v48
	v_lshl_add_u64 v[54:55], v[56:57], 2, s[42:43]
	v_add_f32_e32 v56, 1.0, v61
	v_rcp_f32_e32 v56, v56
	v_sqrt_f32_e32 v57, v48
	v_add_f32_e32 v48, 1.0, v50
	v_rcp_f32_e32 v61, v48
	v_mul_f32_e32 v48, v56, v72
	v_add_f32_e32 v50, v48, v48
	v_cmp_ngt_f32_e32 vcc, s9, v50
	s_waitcnt lgkmcnt(0)
	v_lshlrev_b32_e32 v56, 16, v60
	v_mul_f32_e32 v56, v61, v56
	v_mul_f32_e32 v56, v57, v56
	v_cvt_pk_bf16_f32 v49, v49, v56
	v_mov_b32_e32 v195, v49
	s_and_saveexec_b64 s[2:3], vcc
	s_xor_b64 s[2:3], exec, s[2:3]
	v_fmamk_f32 v49, v50, 0x3ab60b61, v169
	v_fmaak_f32 v49, v50, v49, 0x3d2aaaab
	v_fmaak_f32 v49, v50, v49, 0x3e2aaaab
	v_fma_f32 v49, v50, v49, 0.5
	v_fma_f32 v49, v50, v49, 1.0
	v_mul_f32_e64 v49, v49, -v50
	s_andn2_saveexec_b64 s[2:3], s[2:3]
	v_mul_f32_e32 v49, 0x3fb8aa3b, v50
	v_exp_f32_e32 v49, v49
	s_nop 0
	v_sub_f32_e32 v49, 1.0, v49
	s_or_b64 exec, exec, s[2:3]
	ds_read_u16 v54, v178 offset:464
	v_add_f32_e32 v44, v44, v83
	v_add_f32_e32 v55, v51, v67
	v_mul_f32_e32 v44, 0xbfb8aa3b, v44
	v_mul_f32_e32 v55, 0xbfb8aa3b, v55
	v_exp_f32_e32 v44, v44
	v_exp_f32_e32 v55, v55
	v_max_f32_e32 v49, v49, v49
	v_max_f32_e32 v49, 0, v49
	v_add_f32_e32 v44, 1.0, v44
	v_rcp_f32_e32 v44, v44
	v_sqrt_f32_e32 v56, v49
	v_add_f32_e32 v49, 1.0, v55
	v_rcp_f32_e32 v55, v49
	v_mul_f32_e32 v44, v44, v84
	v_lshl_add_u64 v[50:51], v[58:59], 0, v[52:53]
	v_add_f32_e32 v49, v44, v44
	v_lshl_add_u64 v[50:51], v[50:51], 2, s[42:43]
	v_cmp_ngt_f32_e32 vcc, s9, v49
	s_waitcnt lgkmcnt(0)
	v_lshlrev_b32_e32 v54, 16, v54
	v_mul_f32_e32 v54, v55, v54
	v_mul_f32_e32 v54, v56, v54
	v_cvt_pk_bf16_f32 v48, v48, v54
	v_mov_b32_e32 v196, v48
	s_and_saveexec_b64 s[2:3], vcc
	s_xor_b64 s[2:3], exec, s[2:3]
	v_fmamk_f32 v48, v49, 0x3ab60b61, v169
	v_fmaak_f32 v48, v49, v48, 0x3d2aaaab
	v_fmaak_f32 v48, v49, v48, 0x3e2aaaab
	v_fma_f32 v48, v49, v48, 0.5
	v_fma_f32 v48, v49, v48, 1.0
	v_mul_f32_e64 v54, v48, -v49
	s_andn2_saveexec_b64 s[2:3], s[2:3]
	v_mul_f32_e32 v48, 0x3fb8aa3b, v49
	v_exp_f32_e32 v48, v48
	s_nop 0
	v_sub_f32_e32 v54, 1.0, v48
	s_or_b64 exec, exec, s[2:3]
	v_or_b32_e32 v48, 16, v66
	v_ashrrev_i32_e32 v49, 31, v48
	v_lshlrev_b64 v[48:49], 10, v[48:49]
	v_lshl_add_u64 v[56:57], v[48:49], 0, v[64:65]
	v_lshl_add_u64 v[50:51], v[56:57], 1, s[40:41]
	ds_read_u16 v55, v178 offset:2304
	v_add_f32_e32 v40, v40, v82
	v_mul_f32_e32 v40, 0xbfb8aa3b, v40
	v_exp_f32_e32 v40, v40
	v_max_f32_e32 v54, v54, v54
	v_max_f32_e32 v54, 0, v54
	v_sqrt_f32_e32 v54, v54
	v_add_f32_e32 v40, 1.0, v40
	v_rcp_f32_e32 v40, v40
	s_waitcnt lgkmcnt(0)
	v_lshlrev_b32_e32 v55, 16, v55
	v_mul_f32_e32 v40, v40, v55
	v_mul_f32_e32 v40, v54, v40
	v_cvt_pk_bf16_f32 v40, v44, v40
	v_lshl_add_u64 v[54:55], v[56:57], 2, s[42:43]
	v_mov_b32_e32 v197, v40
	v_add_f32_e32 v40, v45, v83
	v_mul_f32_e32 v40, 0xbfb8aa3b, v40
	v_exp_f32_e32 v40, v40
	s_nop 0
	v_add_f32_e32 v40, 1.0, v40
	v_rcp_f32_e32 v40, v40
	s_nop 0
	v_mul_f32_e32 v54, v40, v84
	v_add_f32_e32 v40, v54, v54
	v_cmp_ngt_f32_e32 vcc, s9, v40
	s_and_saveexec_b64 s[2:3], vcc
	s_xor_b64 s[2:3], exec, s[2:3]
	v_fmamk_f32 v44, v40, 0x3ab60b61, v169
	v_fmaak_f32 v44, v40, v44, 0x3d2aaaab
	v_fmaak_f32 v44, v40, v44, 0x3e2aaaab
	v_fma_f32 v44, v40, v44, 0.5
	v_fma_f32 v44, v40, v44, 1.0
	v_mul_f32_e64 v55, v44, -v40
	s_andn2_saveexec_b64 s[2:3], s[2:3]
	v_mul_f32_e32 v40, 0x3fb8aa3b, v40
	v_exp_f32_e32 v40, v40
	s_nop 0
	v_sub_f32_e32 v55, 1.0, v40
	s_or_b64 exec, exec, s[2:3]
	v_add_f32_e32 v40, v41, v82
	v_mul_f32_e32 v40, 0xbfb8aa3b, v40
	v_exp_f32_e32 v40, v40
	v_add_f32_e32 v46, v46, v83
	v_mul_f32_e32 v46, 0xbfb8aa3b, v46
	v_exp_f32_e32 v46, v46
	v_add_f32_e32 v40, 1.0, v40
	v_rcp_f32_e32 v58, v40
	v_or_b32_e32 v40, 17, v66
	v_ashrrev_i32_e32 v41, 31, v40
	v_lshlrev_b64 v[40:41], 10, v[40:41]
	v_lshl_add_u64 v[56:57], v[40:41], 0, v[64:65]
	v_lshl_add_u64 v[44:45], v[56:57], 1, s[40:41]
	ds_read_u16 v59, v178 offset:2448
	v_max_f32_e32 v55, v55, v55
	v_max_f32_e32 v55, 0, v55
	v_sqrt_f32_e32 v55, v55
	v_add_f32_e32 v46, 1.0, v46
	v_rcp_f32_e32 v46, v46
	s_waitcnt lgkmcnt(0)
;   __host__ __device__ __forceinline__ bf16_t* XC() const { return (bf16_t*)(wsl() + OFF_FFN); }
; __device__ __forceinline__ float bf2f(bf16_t h) { return __uint_as_float(((uint32_t)h) << 16); }
; __device__ __forceinline__ uint32_t pack2(float a, float b) { uint32_t r; asm("v_cvt_pk_bf16_f32 %0, %1, %2" : "=v"(r) : "v"(a), "v"(b)); return r; }
; __device__ __forceinline__ float sigmoidf_(float x) { return __builtin_amdgcn_rcpf(1.0f + __expf(-x)); }
; template <int EPI>
; __device__ __forceinline__ void gemm_tile(const Params& p, const EpiArgs& ea, const bf16_t* __restrict__ A, int lda,
;                                           const bf16_t* __restrict__ Bt, int K, int m0, int n0, char* smem) {
;     ...
;       for (int nh = 0; nh < 2; ++nh) {
;         int ch = (n0 >> 1) + wn * 32 + nh * 16 + fr;
;         float ba = p.lru_b_a[ea.dir * 1024 + ch], bx = p.lru_b_x[ea.dir * 1024 + ch];
;         float sp8 = -8.0f * log1pf(__expf(-p.lru_lam[ea.dir * 1024 + ch]));
; #pragma unroll
;         for (int j = 0; j < 4; ++j) {
;           float r = sigmoidf_(acc[mi][nh * 2][j] + ba);
;           float ig = sigmoidf_(acc[mi][nh * 2 + 1][j] + bx);
;           float la = r * sp8;
;           float x2 = 2.0f * la;
;           float poly = -x2 * (1.0f + x2 * (0.5f + x2 * (0.16666667f + x2 * (0.041666668f + x2 * (0.008333334f + x2 * 0.0013888889f)))));
;           float em = (x2 < -0.3f) ? (1.0f - __expf(x2)) : poly;
;           float u = bf2f(p.XC()[(size_t)(r0 + j) * D + ch]);
;           float inp = __builtin_amdgcn_sqrtf(fmaxf(em, 0.0f)) * (ig * u);
;           ea.outu[(size_t)(r0 + j) * D + ch] = pack2(la, inp);
;         }
;       }
	v_lshlrev_b32_e32 v59, 16, v59
	v_mul_f32_e32 v58, v58, v59
	v_mul_f32_e32 v55, v55, v58
	v_cvt_pk_bf16_f32 v58, v54, v55
	v_lshl_add_u64 v[54:55], v[56:57], 2, s[42:43]
	v_mul_f32_e32 v46, v46, v84
	v_mov_b32_e32 v198, v58
	v_add_f32_e32 v54, v46, v46
	v_cmp_ngt_f32_e32 vcc, s9, v54
	s_and_saveexec_b64 s[2:3], vcc
	s_xor_b64 s[2:3], exec, s[2:3]
	v_fmamk_f32 v55, v54, 0x3ab60b61, v169
	v_fmaak_f32 v55, v54, v55, 0x3d2aaaab
	v_fmaak_f32 v55, v54, v55, 0x3e2aaaab
	v_fma_f32 v55, v54, v55, 0.5
	v_fma_f32 v55, v54, v55, 1.0
	v_mul_f32_e64 v58, v55, -v54
	s_andn2_saveexec_b64 s[2:3], s[2:3]
	v_mul_f32_e32 v54, 0x3fb8aa3b, v54
	v_exp_f32_e32 v54, v54
	s_nop 0
	v_sub_f32_e32 v58, 1.0, v54
	s_or_b64 exec, exec, s[2:3]
	v_or_b32_e32 v54, 18, v66
	v_ashrrev_i32_e32 v55, 31, v54
	v_lshlrev_b64 v[54:55], 10, v[54:55]
	v_lshl_add_u64 v[60:61], v[54:55], 0, v[64:65]
	v_lshl_add_u64 v[56:57], v[60:61], 1, s[40:41]
	ds_read_u16 v59, v178 offset:2592
	v_add_f32_e32 v47, v47, v83
	v_mul_f32_e32 v47, 0xbfb8aa3b, v47
	v_add_f32_e32 v42, v42, v82
	v_exp_f32_e32 v47, v47
	v_mul_f32_e32 v42, 0xbfb8aa3b, v42
	v_exp_f32_e32 v42, v42
	v_max_f32_e32 v58, v58, v58
	v_add_f32_e32 v47, 1.0, v47
	v_rcp_f32_e32 v47, v47
	v_add_f32_e32 v42, 1.0, v42
	v_max_f32_e32 v58, 0, v58
	v_rcp_f32_e32 v63, v42
	v_sqrt_f32_e32 v62, v58
	v_mul_f32_e32 v58, v47, v84
	v_add_f32_e32 v42, v58, v58
	v_lshl_add_u64 v[60:61], v[60:61], 2, s[42:43]
	v_cmp_ngt_f32_e32 vcc, s9, v42
	s_waitcnt lgkmcnt(0)
	v_lshlrev_b32_e32 v47, 16, v59
	v_mul_f32_e32 v47, v63, v47
	v_mul_f32_e32 v47, v62, v47
	v_cvt_pk_bf16_f32 v46, v46, v47
	v_mov_b32_e32 v199, v46
	s_and_saveexec_b64 s[2:3], vcc
	s_xor_b64 s[2:3], exec, s[2:3]
	v_fmamk_f32 v46, v42, 0x3ab60b61, v169
	v_fmaak_f32 v46, v42, v46, 0x3d2aaaab
	v_fmaak_f32 v46, v42, v46, 0x3e2aaaab
	v_fma_f32 v46, v42, v46, 0.5
	v_fma_f32 v46, v42, v46, 1.0
	v_mul_f32_e64 v59, v46, -v42
	s_andn2_saveexec_b64 s[2:3], s[2:3]
	v_mul_f32_e32 v42, 0x3fb8aa3b, v42
	v_exp_f32_e32 v42, v42
	s_nop 0
	v_sub_f32_e32 v59, 1.0, v42
	s_or_b64 exec, exec, s[2:3]
	v_add_f32_e32 v42, v43, v82
	v_mul_f32_e32 v42, 0xbfb8aa3b, v42
	v_exp_f32_e32 v42, v42
	v_add_f32_e32 v36, v36, v74
	v_mul_f32_e32 v36, 0xbfb8aa3b, v36
	v_exp_f32_e32 v36, v36
	v_add_f32_e32 v42, 1.0, v42
	v_rcp_f32_e32 v62, v42
	v_or_b32_e32 v42, 19, v66
	v_ashrrev_i32_e32 v43, 31, v42
	v_lshlrev_b64 v[42:43], 10, v[42:43]
	v_lshl_add_u64 v[60:61], v[42:43], 0, v[64:65]
	v_lshl_add_u64 v[46:47], v[60:61], 1, s[40:41]
	ds_read_u16 v63, v178 offset:2736
	v_max_f32_e32 v59, v59, v59
	v_max_f32_e32 v59, 0, v59
	v_sqrt_f32_e32 v59, v59
	v_add_f32_e32 v36, 1.0, v36
	v_rcp_f32_e32 v36, v36
	s_waitcnt lgkmcnt(0)
	v_lshlrev_b32_e32 v63, 16, v63
	v_mul_f32_e32 v62, v62, v63
	v_mul_f32_e32 v59, v59, v62
	v_cvt_pk_bf16_f32 v62, v58, v59
	v_lshl_add_u64 v[58:59], v[60:61], 2, s[42:43]
	v_mul_f32_e32 v36, v36, v72
	v_mov_b32_e32 v200, v62
	v_add_f32_e32 v58, v36, v36
	v_cmp_ngt_f32_e32 vcc, s9, v58
	s_and_saveexec_b64 s[2:3], vcc
	s_xor_b64 s[2:3], exec, s[2:3]
	v_fmamk_f32 v59, v58, 0x3ab60b61, v169
	v_fmaak_f32 v59, v58, v59, 0x3d2aaaab
	v_fmaak_f32 v59, v58, v59, 0x3e2aaaab
	v_fma_f32 v59, v58, v59, 0.5
	v_fma_f32 v59, v58, v59, 1.0
	v_mul_f32_e64 v59, v59, -v58
	s_andn2_saveexec_b64 s[2:3], s[2:3]
	v_mul_f32_e32 v58, 0x3fb8aa3b, v58
	v_exp_f32_e32 v58, v58
	s_nop 0
	v_sub_f32_e32 v59, 1.0, v58
	s_or_b64 exec, exec, s[2:3]
	ds_read_u16 v50, v178 offset:2336
	v_add_f32_e32 v37, v37, v74
	v_add_f32_e32 v32, v32, v67
	v_mul_f32_e32 v37, 0xbfb8aa3b, v37
	v_mul_f32_e32 v32, 0xbfb8aa3b, v32
	v_exp_f32_e32 v37, v37
	v_exp_f32_e32 v32, v32
	v_max_f32_e32 v51, v59, v59
	v_max_f32_e32 v51, 0, v51
	v_add_f32_e32 v37, 1.0, v37
	v_rcp_f32_e32 v37, v37
	v_add_f32_e32 v32, 1.0, v32
	v_rcp_f32_e32 v58, v32
	v_sqrt_f32_e32 v51, v51
	v_mul_f32_e32 v32, v37, v72
	v_lshl_add_u64 v[48:49], v[48:49], 0, v[52:53]
	v_add_f32_e32 v37, v32, v32
	v_lshl_add_u64 v[48:49], v[48:49], 2, s[42:43]
	v_cmp_ngt_f32_e32 vcc, s9, v37
	s_waitcnt lgkmcnt(0)
	v_lshlrev_b32_e32 v50, 16, v50
	v_mul_f32_e32 v50, v58, v50
	v_mul_f32_e32 v50, v51, v50
	v_cvt_pk_bf16_f32 v36, v36, v50
	v_mov_b32_e32 v201, v36
	s_and_saveexec_b64 s[2:3], vcc
	s_xor_b64 s[2:3], exec, s[2:3]
	v_fmamk_f32 v36, v37, 0x3ab60b61, v169
	v_fmaak_f32 v36, v37, v36, 0x3d2aaaab
	v_fmaak_f32 v36, v37, v36, 0x3e2aaaab
	v_fma_f32 v36, v37, v36, 0.5
	v_fma_f32 v36, v37, v36, 1.0
	v_mul_f32_e64 v36, v36, -v37
	s_andn2_saveexec_b64 s[2:3], s[2:3]
	v_mul_f32_e32 v36, 0x3fb8aa3b, v37
	v_exp_f32_e32 v36, v36
	s_nop 0
	v_sub_f32_e32 v36, 1.0, v36
	s_or_b64 exec, exec, s[2:3]
	ds_read_u16 v37, v178 offset:2480
	v_add_f32_e32 v38, v38, v74
	v_add_f32_e32 v33, v33, v67
	v_mul_f32_e32 v38, 0xbfb8aa3b, v38
	v_mul_f32_e32 v33, 0xbfb8aa3b, v33
	v_exp_f32_e32 v38, v38
	v_exp_f32_e32 v33, v33
	v_max_f32_e32 v36, v36, v36
	v_max_f32_e32 v36, 0, v36
	v_add_f32_e32 v38, 1.0, v38
	v_rcp_f32_e32 v38, v38
	v_add_f32_e32 v33, 1.0, v33
	v_rcp_f32_e32 v45, v33
	v_sqrt_f32_e32 v44, v36
	v_mul_f32_e32 v33, v38, v72
	v_lshl_add_u64 v[40:41], v[40:41], 0, v[52:53]
	v_add_f32_e32 v36, v33, v33
	v_lshl_add_u64 v[40:41], v[40:41], 2, s[42:43]
	v_cmp_ngt_f32_e32 vcc, s9, v36
	s_waitcnt lgkmcnt(0)
;   __host__ __device__ __forceinline__ bf16_t* XC() const { return (bf16_t*)(wsl() + OFF_FFN); }
; __device__ __forceinline__ float bf2f(bf16_t h) { return __uint_as_float(((uint32_t)h) << 16); }
; __device__ __forceinline__ uint32_t pack2(float a, float b) { uint32_t r; asm("v_cvt_pk_bf16_f32 %0, %1, %2" : "=v"(r) : "v"(a), "v"(b)); return r; }
; __device__ __forceinline__ float sigmoidf_(float x) { return __builtin_amdgcn_rcpf(1.0f + __expf(-x)); }
; template <int EPI>
; __device__ __forceinline__ void gemm_tile(const Params& p, const EpiArgs& ea, const bf16_t* __restrict__ A, int lda,
;                                           const bf16_t* __restrict__ Bt, int K, int m0, int n0, char* smem) {
;     ...
;       for (int nh = 0; nh < 2; ++nh) {
;         int ch = (n0 >> 1) + wn * 32 + nh * 16 + fr;
;         float ba = p.lru_b_a[ea.dir * 1024 + ch], bx = p.lru_b_x[ea.dir * 1024 + ch];
;         float sp8 = -8.0f * log1pf(__expf(-p.lru_lam[ea.dir * 1024 + ch]));
; #pragma unroll
;         for (int j = 0; j < 4; ++j) {
;           float r = sigmoidf_(acc[mi][nh * 2][j] + ba);
;           float ig = sigmoidf_(acc[mi][nh * 2 + 1][j] + bx);
;           float la = r * sp8;
;           float x2 = 2.0f * la;
;           float poly = -x2 * (1.0f + x2 * (0.5f + x2 * (0.16666667f + x2 * (0.041666668f + x2 * (0.008333334f + x2 * 0.0013888889f)))));
;           float em = (x2 < -0.3f) ? (1.0f - __expf(x2)) : poly;
;           float u = bf2f(p.XC()[(size_t)(r0 + j) * D + ch]);
;           float inp = __builtin_amdgcn_sqrtf(fmaxf(em, 0.0f)) * (ig * u);
;           ea.outu[(size_t)(r0 + j) * D + ch] = pack2(la, inp);
;         }
;       }
	v_lshlrev_b32_e32 v37, 16, v37
	v_mul_f32_e32 v37, v45, v37
	v_mul_f32_e32 v37, v44, v37
	v_cvt_pk_bf16_f32 v32, v32, v37
	v_mov_b32_e32 v202, v32
	s_and_saveexec_b64 s[2:3], vcc
	s_xor_b64 s[2:3], exec, s[2:3]
	v_fmamk_f32 v32, v36, 0x3ab60b61, v169
	v_fmaak_f32 v32, v36, v32, 0x3d2aaaab
	v_fmaak_f32 v32, v36, v32, 0x3e2aaaab
	v_fma_f32 v32, v36, v32, 0.5
	v_fma_f32 v32, v36, v32, 1.0
	v_mul_f32_e64 v32, v32, -v36
	s_andn2_saveexec_b64 s[2:3], s[2:3]
	v_mul_f32_e32 v32, 0x3fb8aa3b, v36
	v_exp_f32_e32 v32, v32
	s_nop 0
	v_sub_f32_e32 v32, 1.0, v32
	s_or_b64 exec, exec, s[2:3]
	ds_read_u16 v38, v178 offset:2624
	v_add_f32_e32 v39, v39, v74
	v_add_f32_e32 v34, v34, v67
	v_mul_f32_e32 v39, 0xbfb8aa3b, v39
	v_mul_f32_e32 v34, 0xbfb8aa3b, v34
	v_exp_f32_e32 v39, v39
	v_exp_f32_e32 v34, v34
	v_max_f32_e32 v32, v32, v32
	v_max_f32_e32 v32, 0, v32
	v_add_f32_e32 v39, 1.0, v39
	v_rcp_f32_e32 v39, v39
	v_sqrt_f32_e32 v40, v32
	v_add_f32_e32 v32, 1.0, v34
	v_rcp_f32_e32 v41, v32
	v_mul_f32_e32 v32, v39, v72
	v_lshl_add_u64 v[36:37], v[54:55], 0, v[52:53]
	v_add_f32_e32 v34, v32, v32
	v_lshl_add_u64 v[36:37], v[36:37], 2, s[42:43]
	v_cmp_ngt_f32_e32 vcc, s9, v34
	s_waitcnt lgkmcnt(0)
	v_lshlrev_b32_e32 v38, 16, v38
	v_mul_f32_e32 v38, v41, v38
	v_mul_f32_e32 v38, v40, v38
	v_cvt_pk_bf16_f32 v33, v33, v38
	v_mov_b32_e32 v203, v33
	s_and_saveexec_b64 s[2:3], vcc
	s_xor_b64 s[2:3], exec, s[2:3]
	v_fmamk_f32 v33, v34, 0x3ab60b61, v169
	v_fmaak_f32 v33, v34, v33, 0x3d2aaaab
	v_fmaak_f32 v33, v34, v33, 0x3e2aaaab
	v_fma_f32 v33, v34, v33, 0.5
	v_fma_f32 v33, v34, v33, 1.0
	v_mul_f32_e64 v33, v33, -v34
	s_andn2_saveexec_b64 s[2:3], s[2:3]
	v_mul_f32_e32 v33, 0x3fb8aa3b, v34
	v_exp_f32_e32 v33, v33
	s_nop 0
	v_sub_f32_e32 v33, 1.0, v33
	s_or_b64 exec, exec, s[2:3]
	ds_read_u16 v36, v178 offset:2768
	v_add_f32_e32 v28, v28, v83
	v_add_f32_e32 v37, v35, v67
	v_mul_f32_e32 v28, 0xbfb8aa3b, v28
	v_mul_f32_e32 v37, 0xbfb8aa3b, v37
	v_exp_f32_e32 v28, v28
	v_exp_f32_e32 v37, v37
	v_max_f32_e32 v33, v33, v33
	v_max_f32_e32 v33, 0, v33
	v_add_f32_e32 v28, 1.0, v28
	v_rcp_f32_e32 v28, v28
	v_sqrt_f32_e32 v38, v33
	v_add_f32_e32 v33, 1.0, v37
	v_rcp_f32_e32 v37, v33
	v_mul_f32_e32 v28, v28, v84
	v_lshl_add_u64 v[34:35], v[42:43], 0, v[52:53]
	v_add_f32_e32 v33, v28, v28
	v_lshl_add_u64 v[34:35], v[34:35], 2, s[42:43]
	v_cmp_ngt_f32_e32 vcc, s9, v33
	s_waitcnt lgkmcnt(0)
	v_lshlrev_b32_e32 v36, 16, v36
	v_mul_f32_e32 v36, v37, v36
	v_mul_f32_e32 v36, v38, v36
	v_cvt_pk_bf16_f32 v32, v32, v36
	v_mov_b32_e32 v204, v32
	s_and_saveexec_b64 s[2:3], vcc
	s_xor_b64 s[2:3], exec, s[2:3]
	v_fmamk_f32 v32, v33, 0x3ab60b61, v169
	v_fmaak_f32 v32, v33, v32, 0x3d2aaaab
	v_fmaak_f32 v32, v33, v32, 0x3e2aaaab
	v_fma_f32 v32, v33, v32, 0.5
	v_fma_f32 v32, v33, v32, 1.0
	v_mul_f32_e64 v36, v32, -v33
	s_andn2_saveexec_b64 s[2:3], s[2:3]
	v_mul_f32_e32 v32, 0x3fb8aa3b, v33
	v_exp_f32_e32 v32, v32
	s_nop 0
	v_sub_f32_e32 v36, 1.0, v32
	s_or_b64 exec, exec, s[2:3]
	v_or_b32_e32 v32, 32, v66
	v_ashrrev_i32_e32 v33, 31, v32
	v_lshlrev_b64 v[32:33], 10, v[32:33]
	v_lshl_add_u64 v[38:39], v[32:33], 0, v[64:65]
	v_lshl_add_u64 v[34:35], v[38:39], 1, s[40:41]
	ds_read_u16 v37, v178 offset:4608
	v_add_f32_e32 v24, v24, v82
	v_mul_f32_e32 v24, 0xbfb8aa3b, v24
	v_exp_f32_e32 v24, v24
	v_max_f32_e32 v36, v36, v36
	v_max_f32_e32 v36, 0, v36
	v_sqrt_f32_e32 v36, v36
	v_add_f32_e32 v24, 1.0, v24
	v_rcp_f32_e32 v24, v24
	s_waitcnt lgkmcnt(0)
	v_lshlrev_b32_e32 v37, 16, v37
	v_mul_f32_e32 v24, v24, v37
	v_mul_f32_e32 v24, v36, v24
	v_cvt_pk_bf16_f32 v24, v28, v24
	v_lshl_add_u64 v[36:37], v[38:39], 2, s[42:43]
	v_mov_b32_e32 v205, v24
	v_add_f32_e32 v24, v29, v83
	v_mul_f32_e32 v24, 0xbfb8aa3b, v24
	v_exp_f32_e32 v24, v24
	s_nop 0
	v_add_f32_e32 v24, 1.0, v24
	v_rcp_f32_e32 v24, v24
	s_nop 0
	v_mul_f32_e32 v36, v24, v84
	v_add_f32_e32 v24, v36, v36
	v_cmp_ngt_f32_e32 vcc, s9, v24
	s_and_saveexec_b64 s[2:3], vcc
	s_xor_b64 s[2:3], exec, s[2:3]
	v_fmamk_f32 v28, v24, 0x3ab60b61, v169
	v_fmaak_f32 v28, v24, v28, 0x3d2aaaab
	v_fmaak_f32 v28, v24, v28, 0x3e2aaaab
	v_fma_f32 v28, v24, v28, 0.5
	v_fma_f32 v28, v24, v28, 1.0
	v_mul_f32_e64 v37, v28, -v24
	s_andn2_saveexec_b64 s[2:3], s[2:3]
	v_mul_f32_e32 v24, 0x3fb8aa3b, v24
	v_exp_f32_e32 v24, v24
	s_nop 0
	v_sub_f32_e32 v37, 1.0, v24
	s_or_b64 exec, exec, s[2:3]
	v_add_f32_e32 v24, v25, v82
	v_mul_f32_e32 v24, 0xbfb8aa3b, v24
	v_exp_f32_e32 v24, v24
	v_add_f32_e32 v30, v30, v83
	v_mul_f32_e32 v30, 0xbfb8aa3b, v30
	v_exp_f32_e32 v30, v30
	v_add_f32_e32 v24, 1.0, v24
	v_rcp_f32_e32 v40, v24
	v_or_b32_e32 v24, 33, v66
	v_ashrrev_i32_e32 v25, 31, v24
	v_lshlrev_b64 v[24:25], 10, v[24:25]
	v_lshl_add_u64 v[38:39], v[24:25], 0, v[64:65]
	v_lshl_add_u64 v[28:29], v[38:39], 1, s[40:41]
	ds_read_u16 v41, v178 offset:4752
	v_max_f32_e32 v37, v37, v37
	v_max_f32_e32 v37, 0, v37
	v_sqrt_f32_e32 v37, v37
	v_add_f32_e32 v30, 1.0, v30
	v_rcp_f32_e32 v30, v30
	s_waitcnt lgkmcnt(0)
;   __host__ __device__ __forceinline__ bf16_t* XC() const { return (bf16_t*)(wsl() + OFF_FFN); }
; __device__ __forceinline__ float bf2f(bf16_t h) { return __uint_as_float(((uint32_t)h) << 16); }
; __device__ __forceinline__ uint32_t pack2(float a, float b) { uint32_t r; asm("v_cvt_pk_bf16_f32 %0, %1, %2" : "=v"(r) : "v"(a), "v"(b)); return r; }
; __device__ __forceinline__ float sigmoidf_(float x) { return __builtin_amdgcn_rcpf(1.0f + __expf(-x)); }
; template <int EPI>
; __device__ __forceinline__ void gemm_tile(const Params& p, const EpiArgs& ea, const bf16_t* __restrict__ A, int lda,
;                                           const bf16_t* __restrict__ Bt, int K, int m0, int n0, char* smem) {
;     ...
;       for (int nh = 0; nh < 2; ++nh) {
;         int ch = (n0 >> 1) + wn * 32 + nh * 16 + fr;
;         float ba = p.lru_b_a[ea.dir * 1024 + ch], bx = p.lru_b_x[ea.dir * 1024 + ch];
;         float sp8 = -8.0f * log1pf(__expf(-p.lru_lam[ea.dir * 1024 + ch]));
; #pragma unroll
;         for (int j = 0; j < 4; ++j) {
;           float r = sigmoidf_(acc[mi][nh * 2][j] + ba);
;           float ig = sigmoidf_(acc[mi][nh * 2 + 1][j] + bx);
;           float la = r * sp8;
;           float x2 = 2.0f * la;
;           float poly = -x2 * (1.0f + x2 * (0.5f + x2 * (0.16666667f + x2 * (0.041666668f + x2 * (0.008333334f + x2 * 0.0013888889f)))));
;           float em = (x2 < -0.3f) ? (1.0f - __expf(x2)) : poly;
;           float u = bf2f(p.XC()[(size_t)(r0 + j) * D + ch]);
;           float inp = __builtin_amdgcn_sqrtf(fmaxf(em, 0.0f)) * (ig * u);
;           ea.outu[(size_t)(r0 + j) * D + ch] = pack2(la, inp);
;         }
;       }
	v_lshlrev_b32_e32 v41, 16, v41
	v_mul_f32_e32 v40, v40, v41
	v_mul_f32_e32 v37, v37, v40
	v_cvt_pk_bf16_f32 v40, v36, v37
	v_lshl_add_u64 v[36:37], v[38:39], 2, s[42:43]
	v_mul_f32_e32 v30, v30, v84
	v_mov_b32_e32 v206, v40
	v_add_f32_e32 v36, v30, v30
	v_cmp_ngt_f32_e32 vcc, s9, v36
	s_and_saveexec_b64 s[2:3], vcc
	s_xor_b64 s[2:3], exec, s[2:3]
	v_fmamk_f32 v37, v36, 0x3ab60b61, v169
	v_fmaak_f32 v37, v36, v37, 0x3d2aaaab
	v_fmaak_f32 v37, v36, v37, 0x3e2aaaab
	v_fma_f32 v37, v36, v37, 0.5
	v_fma_f32 v37, v36, v37, 1.0
	v_mul_f32_e64 v40, v37, -v36
	s_andn2_saveexec_b64 s[2:3], s[2:3]
	v_mul_f32_e32 v36, 0x3fb8aa3b, v36
	v_exp_f32_e32 v36, v36
	s_nop 0
	v_sub_f32_e32 v40, 1.0, v36
	s_or_b64 exec, exec, s[2:3]
	v_or_b32_e32 v36, 34, v66
	v_ashrrev_i32_e32 v37, 31, v36
	v_lshlrev_b64 v[36:37], 10, v[36:37]
	v_lshl_add_u64 v[42:43], v[36:37], 0, v[64:65]
	v_lshl_add_u64 v[38:39], v[42:43], 1, s[40:41]
	ds_read_u16 v41, v178 offset:4896
	v_add_f32_e32 v31, v31, v83
	v_mul_f32_e32 v31, 0xbfb8aa3b, v31
	v_add_f32_e32 v26, v26, v82
	v_exp_f32_e32 v31, v31
	v_mul_f32_e32 v26, 0xbfb8aa3b, v26
	v_exp_f32_e32 v26, v26
	v_max_f32_e32 v40, v40, v40
	v_add_f32_e32 v31, 1.0, v31
	v_rcp_f32_e32 v31, v31
	v_add_f32_e32 v26, 1.0, v26
	v_max_f32_e32 v40, 0, v40
	v_rcp_f32_e32 v45, v26
	v_sqrt_f32_e32 v44, v40
	v_mul_f32_e32 v40, v31, v84
	v_add_f32_e32 v26, v40, v40
	v_lshl_add_u64 v[42:43], v[42:43], 2, s[42:43]
	v_cmp_ngt_f32_e32 vcc, s9, v26
	s_waitcnt lgkmcnt(0)
	v_lshlrev_b32_e32 v31, 16, v41
	v_mul_f32_e32 v31, v45, v31
	v_mul_f32_e32 v31, v44, v31
	v_cvt_pk_bf16_f32 v30, v30, v31
	v_mov_b32_e32 v207, v30
	s_and_saveexec_b64 s[2:3], vcc
	s_xor_b64 s[2:3], exec, s[2:3]
	v_fmamk_f32 v30, v26, 0x3ab60b61, v169
	v_fmaak_f32 v30, v26, v30, 0x3d2aaaab
	v_fmaak_f32 v30, v26, v30, 0x3e2aaaab
	v_fma_f32 v30, v26, v30, 0.5
	v_fma_f32 v30, v26, v30, 1.0
	v_mul_f32_e64 v41, v30, -v26
	s_andn2_saveexec_b64 s[2:3], s[2:3]
	v_mul_f32_e32 v26, 0x3fb8aa3b, v26
	v_exp_f32_e32 v26, v26
	s_nop 0
	v_sub_f32_e32 v41, 1.0, v26
	s_or_b64 exec, exec, s[2:3]
	v_add_f32_e32 v26, v27, v82
	v_mul_f32_e32 v26, 0xbfb8aa3b, v26
	v_exp_f32_e32 v26, v26
	v_add_f32_e32 v20, v20, v74
	v_mul_f32_e32 v20, 0xbfb8aa3b, v20
	v_exp_f32_e32 v20, v20
	v_add_f32_e32 v26, 1.0, v26
	v_rcp_f32_e32 v44, v26
	v_or_b32_e32 v26, 35, v66
	v_ashrrev_i32_e32 v27, 31, v26
	v_lshlrev_b64 v[26:27], 10, v[26:27]
	v_lshl_add_u64 v[42:43], v[26:27], 0, v[64:65]
	v_lshl_add_u64 v[30:31], v[42:43], 1, s[40:41]
	ds_read_u16 v45, v178 offset:5040
	v_max_f32_e32 v41, v41, v41
	v_max_f32_e32 v41, 0, v41
	v_sqrt_f32_e32 v41, v41
	v_add_f32_e32 v20, 1.0, v20
	v_rcp_f32_e32 v20, v20
	s_waitcnt lgkmcnt(0)
	v_lshlrev_b32_e32 v45, 16, v45
	v_mul_f32_e32 v44, v44, v45
	v_mul_f32_e32 v41, v41, v44
	v_cvt_pk_bf16_f32 v44, v40, v41
	v_lshl_add_u64 v[40:41], v[42:43], 2, s[42:43]
	v_mul_f32_e32 v20, v20, v72
	v_mov_b32_e32 v208, v44
	v_add_f32_e32 v40, v20, v20
	v_cmp_ngt_f32_e32 vcc, s9, v40
	s_and_saveexec_b64 s[2:3], vcc
	s_xor_b64 s[2:3], exec, s[2:3]
	v_fmamk_f32 v41, v40, 0x3ab60b61, v169
	v_fmaak_f32 v41, v40, v41, 0x3d2aaaab
	v_fmaak_f32 v41, v40, v41, 0x3e2aaaab
	v_fma_f32 v41, v40, v41, 0.5
	v_fma_f32 v41, v40, v41, 1.0
	v_mul_f32_e64 v41, v41, -v40
	s_andn2_saveexec_b64 s[2:3], s[2:3]
	v_mul_f32_e32 v40, 0x3fb8aa3b, v40
	v_exp_f32_e32 v40, v40
	s_nop 0
	v_sub_f32_e32 v41, 1.0, v40
	s_or_b64 exec, exec, s[2:3]
	ds_read_u16 v34, v178 offset:4640
	v_add_f32_e32 v21, v21, v74
	v_add_f32_e32 v16, v16, v67
	v_mul_f32_e32 v21, 0xbfb8aa3b, v21
	v_mul_f32_e32 v16, 0xbfb8aa3b, v16
	v_exp_f32_e32 v21, v21
	v_exp_f32_e32 v16, v16
	v_max_f32_e32 v35, v41, v41
	v_max_f32_e32 v35, 0, v35
	v_add_f32_e32 v21, 1.0, v21
	v_rcp_f32_e32 v21, v21
	v_add_f32_e32 v16, 1.0, v16
	v_rcp_f32_e32 v40, v16
	v_sqrt_f32_e32 v35, v35
	v_mul_f32_e32 v16, v21, v72
	v_lshl_add_u64 v[32:33], v[32:33], 0, v[52:53]
	v_add_f32_e32 v21, v16, v16
	v_lshl_add_u64 v[32:33], v[32:33], 2, s[42:43]
	v_cmp_ngt_f32_e32 vcc, s9, v21
	s_waitcnt lgkmcnt(0)
	v_lshlrev_b32_e32 v34, 16, v34
	v_mul_f32_e32 v34, v40, v34
	v_mul_f32_e32 v34, v35, v34
	v_cvt_pk_bf16_f32 v20, v20, v34
	v_mov_b32_e32 v209, v20
	s_and_saveexec_b64 s[2:3], vcc
	s_xor_b64 s[2:3], exec, s[2:3]
	v_fmamk_f32 v20, v21, 0x3ab60b61, v169
	v_fmaak_f32 v20, v21, v20, 0x3d2aaaab
	v_fmaak_f32 v20, v21, v20, 0x3e2aaaab
	v_fma_f32 v20, v21, v20, 0.5
	v_fma_f32 v20, v21, v20, 1.0
	v_mul_f32_e64 v20, v20, -v21
	s_andn2_saveexec_b64 s[2:3], s[2:3]
	v_mul_f32_e32 v20, 0x3fb8aa3b, v21
	v_exp_f32_e32 v20, v20
	s_nop 0
	v_sub_f32_e32 v20, 1.0, v20
	s_or_b64 exec, exec, s[2:3]
	ds_read_u16 v21, v178 offset:4784
	v_add_f32_e32 v22, v22, v74
	v_add_f32_e32 v17, v17, v67
	v_mul_f32_e32 v22, 0xbfb8aa3b, v22
	v_mul_f32_e32 v17, 0xbfb8aa3b, v17
	v_exp_f32_e32 v22, v22
	v_exp_f32_e32 v17, v17
	v_max_f32_e32 v20, v20, v20
	v_max_f32_e32 v20, 0, v20
	v_add_f32_e32 v22, 1.0, v22
	v_rcp_f32_e32 v22, v22
	v_add_f32_e32 v17, 1.0, v17
	v_rcp_f32_e32 v29, v17
	v_sqrt_f32_e32 v28, v20
	v_mul_f32_e32 v17, v22, v72
	v_lshl_add_u64 v[24:25], v[24:25], 0, v[52:53]
	v_add_f32_e32 v20, v17, v17
	v_lshl_add_u64 v[24:25], v[24:25], 2, s[42:43]
	v_cmp_ngt_f32_e32 vcc, s9, v20
	s_waitcnt lgkmcnt(0)
;   __host__ __device__ __forceinline__ bf16_t* XC() const { return (bf16_t*)(wsl() + OFF_FFN); }
; __device__ __forceinline__ float bf2f(bf16_t h) { return __uint_as_float(((uint32_t)h) << 16); }
; __device__ __forceinline__ uint32_t pack2(float a, float b) { uint32_t r; asm("v_cvt_pk_bf16_f32 %0, %1, %2" : "=v"(r) : "v"(a), "v"(b)); return r; }
; __device__ __forceinline__ float sigmoidf_(float x) { return __builtin_amdgcn_rcpf(1.0f + __expf(-x)); }
; template <int EPI>
; __device__ __forceinline__ void gemm_tile(const Params& p, const EpiArgs& ea, const bf16_t* __restrict__ A, int lda,
;                                           const bf16_t* __restrict__ Bt, int K, int m0, int n0, char* smem) {
;     ...
;       for (int nh = 0; nh < 2; ++nh) {
;         int ch = (n0 >> 1) + wn * 32 + nh * 16 + fr;
;         float ba = p.lru_b_a[ea.dir * 1024 + ch], bx = p.lru_b_x[ea.dir * 1024 + ch];
;         float sp8 = -8.0f * log1pf(__expf(-p.lru_lam[ea.dir * 1024 + ch]));
; #pragma unroll
;         for (int j = 0; j < 4; ++j) {
;           float r = sigmoidf_(acc[mi][nh * 2][j] + ba);
;           float ig = sigmoidf_(acc[mi][nh * 2 + 1][j] + bx);
;           float la = r * sp8;
;           float x2 = 2.0f * la;
;           float poly = -x2 * (1.0f + x2 * (0.5f + x2 * (0.16666667f + x2 * (0.041666668f + x2 * (0.008333334f + x2 * 0.0013888889f)))));
;           float em = (x2 < -0.3f) ? (1.0f - __expf(x2)) : poly;
;           float u = bf2f(p.XC()[(size_t)(r0 + j) * D + ch]);
;           float inp = __builtin_amdgcn_sqrtf(fmaxf(em, 0.0f)) * (ig * u);
;           ea.outu[(size_t)(r0 + j) * D + ch] = pack2(la, inp);
;         }
;       }
	v_lshlrev_b32_e32 v21, 16, v21
	v_mul_f32_e32 v21, v29, v21
	v_mul_f32_e32 v21, v28, v21
	v_cvt_pk_bf16_f32 v16, v16, v21
	v_mov_b32_e32 v210, v16
	s_and_saveexec_b64 s[2:3], vcc
	s_xor_b64 s[2:3], exec, s[2:3]
	v_fmamk_f32 v16, v20, 0x3ab60b61, v169
	v_fmaak_f32 v16, v20, v16, 0x3d2aaaab
	v_fmaak_f32 v16, v20, v16, 0x3e2aaaab
	v_fma_f32 v16, v20, v16, 0.5
	v_fma_f32 v16, v20, v16, 1.0
	v_mul_f32_e64 v16, v16, -v20
	s_andn2_saveexec_b64 s[2:3], s[2:3]
	v_mul_f32_e32 v16, 0x3fb8aa3b, v20
	v_exp_f32_e32 v16, v16
	s_nop 0
	v_sub_f32_e32 v16, 1.0, v16
	s_or_b64 exec, exec, s[2:3]
	ds_read_u16 v22, v178 offset:4928
	v_add_f32_e32 v23, v23, v74
	v_add_f32_e32 v18, v18, v67
	v_mul_f32_e32 v23, 0xbfb8aa3b, v23
	v_mul_f32_e32 v18, 0xbfb8aa3b, v18
	v_exp_f32_e32 v23, v23
	v_exp_f32_e32 v18, v18
	v_max_f32_e32 v16, v16, v16
	v_max_f32_e32 v16, 0, v16
	v_add_f32_e32 v23, 1.0, v23
	v_rcp_f32_e32 v23, v23
	v_sqrt_f32_e32 v24, v16
	v_add_f32_e32 v16, 1.0, v18
	v_rcp_f32_e32 v25, v16
	v_mul_f32_e32 v16, v23, v72
	v_lshl_add_u64 v[20:21], v[36:37], 0, v[52:53]
	v_add_f32_e32 v18, v16, v16
	v_lshl_add_u64 v[20:21], v[20:21], 2, s[42:43]
	v_cmp_ngt_f32_e32 vcc, s9, v18
	s_waitcnt lgkmcnt(0)
	v_lshlrev_b32_e32 v22, 16, v22
	v_mul_f32_e32 v22, v25, v22
	v_mul_f32_e32 v22, v24, v22
	v_cvt_pk_bf16_f32 v17, v17, v22
	v_mov_b32_e32 v211, v17
	s_and_saveexec_b64 s[2:3], vcc
	s_xor_b64 s[2:3], exec, s[2:3]
	v_fmamk_f32 v17, v18, 0x3ab60b61, v169
	v_fmaak_f32 v17, v18, v17, 0x3d2aaaab
	v_fmaak_f32 v17, v18, v17, 0x3e2aaaab
	v_fma_f32 v17, v18, v17, 0.5
	v_fma_f32 v17, v18, v17, 1.0
	v_mul_f32_e64 v17, v17, -v18
	s_andn2_saveexec_b64 s[2:3], s[2:3]
	v_mul_f32_e32 v17, 0x3fb8aa3b, v18
	v_exp_f32_e32 v17, v17
	s_nop 0
	v_sub_f32_e32 v17, 1.0, v17
	s_or_b64 exec, exec, s[2:3]
	ds_read_u16 v20, v178 offset:5072
	v_add_f32_e32 v12, v12, v83
	v_add_f32_e32 v21, v19, v67
	v_mul_f32_e32 v12, 0xbfb8aa3b, v12
	v_mul_f32_e32 v21, 0xbfb8aa3b, v21
	v_exp_f32_e32 v12, v12
	v_exp_f32_e32 v21, v21
	v_max_f32_e32 v17, v17, v17
	v_max_f32_e32 v17, 0, v17
	v_add_f32_e32 v12, 1.0, v12
	v_rcp_f32_e32 v12, v12
	v_sqrt_f32_e32 v22, v17
	v_add_f32_e32 v17, 1.0, v21
	v_rcp_f32_e32 v21, v17
	v_mul_f32_e32 v12, v12, v84
	v_lshl_add_u64 v[18:19], v[26:27], 0, v[52:53]
	v_add_f32_e32 v17, v12, v12
	v_lshl_add_u64 v[18:19], v[18:19], 2, s[42:43]
	v_cmp_ngt_f32_e32 vcc, s9, v17
	s_waitcnt lgkmcnt(0)
	v_lshlrev_b32_e32 v20, 16, v20
	v_mul_f32_e32 v20, v21, v20
	v_mul_f32_e32 v20, v22, v20
	v_cvt_pk_bf16_f32 v16, v16, v20
	v_mov_b32_e32 v212, v16
	s_and_saveexec_b64 s[2:3], vcc
	s_xor_b64 s[2:3], exec, s[2:3]
	v_fmamk_f32 v16, v17, 0x3ab60b61, v169
	v_fmaak_f32 v16, v17, v16, 0x3d2aaaab
	v_fmaak_f32 v16, v17, v16, 0x3e2aaaab
	v_fma_f32 v16, v17, v16, 0.5
	v_fma_f32 v16, v17, v16, 1.0
	v_mul_f32_e64 v20, v16, -v17
	s_andn2_saveexec_b64 s[2:3], s[2:3]
	v_mul_f32_e32 v16, 0x3fb8aa3b, v17
	v_exp_f32_e32 v16, v16
	s_nop 0
	v_sub_f32_e32 v20, 1.0, v16
	s_or_b64 exec, exec, s[2:3]
	v_or_b32_e32 v16, 48, v66
	v_ashrrev_i32_e32 v17, 31, v16
	v_lshlrev_b64 v[16:17], 10, v[16:17]
	v_lshl_add_u64 v[22:23], v[16:17], 0, v[64:65]
	v_lshl_add_u64 v[18:19], v[22:23], 1, s[40:41]
	ds_read_u16 v21, v178 offset:6912
	v_add_f32_e32 v8, v8, v82
	v_mul_f32_e32 v8, 0xbfb8aa3b, v8
	v_exp_f32_e32 v8, v8
	v_max_f32_e32 v20, v20, v20
	v_max_f32_e32 v20, 0, v20
	v_sqrt_f32_e32 v20, v20
	v_add_f32_e32 v8, 1.0, v8
	v_rcp_f32_e32 v8, v8
	s_waitcnt lgkmcnt(0)
	v_lshlrev_b32_e32 v21, 16, v21
	v_mul_f32_e32 v8, v8, v21
	v_mul_f32_e32 v8, v20, v8
	v_cvt_pk_bf16_f32 v8, v12, v8
	v_lshl_add_u64 v[20:21], v[22:23], 2, s[42:43]
	v_mov_b32_e32 v213, v8
	v_add_f32_e32 v8, v13, v83
	v_mul_f32_e32 v8, 0xbfb8aa3b, v8
	v_exp_f32_e32 v8, v8
	s_nop 0
	v_add_f32_e32 v8, 1.0, v8
	v_rcp_f32_e32 v8, v8
	s_nop 0
	v_mul_f32_e32 v20, v8, v84
	v_add_f32_e32 v8, v20, v20
	v_cmp_ngt_f32_e32 vcc, s9, v8
	s_and_saveexec_b64 s[2:3], vcc
	s_xor_b64 s[2:3], exec, s[2:3]
	v_fmamk_f32 v12, v8, 0x3ab60b61, v169
	v_fmaak_f32 v12, v8, v12, 0x3d2aaaab
	v_fmaak_f32 v12, v8, v12, 0x3e2aaaab
	v_fma_f32 v12, v8, v12, 0.5
	v_fma_f32 v12, v8, v12, 1.0
	v_mul_f32_e64 v21, v12, -v8
	s_andn2_saveexec_b64 s[2:3], s[2:3]
	v_mul_f32_e32 v8, 0x3fb8aa3b, v8
	v_exp_f32_e32 v8, v8
	s_nop 0
	v_sub_f32_e32 v21, 1.0, v8
	s_or_b64 exec, exec, s[2:3]
	v_add_f32_e32 v8, v9, v82
	v_mul_f32_e32 v8, 0xbfb8aa3b, v8
	v_exp_f32_e32 v8, v8
	v_add_f32_e32 v14, v14, v83
	v_mul_f32_e32 v14, 0xbfb8aa3b, v14
	v_exp_f32_e32 v14, v14
	v_add_f32_e32 v8, 1.0, v8
	v_rcp_f32_e32 v24, v8
	v_or_b32_e32 v8, 49, v66
	v_ashrrev_i32_e32 v9, 31, v8
	v_lshlrev_b64 v[8:9], 10, v[8:9]
	v_lshl_add_u64 v[22:23], v[8:9], 0, v[64:65]
	v_lshl_add_u64 v[12:13], v[22:23], 1, s[40:41]
	ds_read_u16 v25, v178 offset:7056
	v_max_f32_e32 v21, v21, v21
	v_max_f32_e32 v21, 0, v21
	v_sqrt_f32_e32 v21, v21
	v_add_f32_e32 v14, 1.0, v14
	v_rcp_f32_e32 v14, v14
	s_waitcnt lgkmcnt(0)
	v_lshlrev_b32_e32 v25, 16, v25
	v_mul_f32_e32 v24, v24, v25
	v_mul_f32_e32 v21, v21, v24
	v_cvt_pk_bf16_f32 v24, v20, v21
	v_lshl_add_u64 v[20:21], v[22:23], 2, s[42:43]
	v_mul_f32_e32 v14, v14, v84
	v_mov_b32_e32 v214, v24
	v_add_f32_e32 v20, v14, v14
	v_cmp_ngt_f32_e32 vcc, s9, v20
	s_and_saveexec_b64 s[2:3], vcc
	s_xor_b64 s[2:3], exec, s[2:3]
	v_fmamk_f32 v21, v20, 0x3ab60b61, v169
	v_fmaak_f32 v21, v20, v21, 0x3d2aaaab
	v_fmaak_f32 v21, v20, v21, 0x3e2aaaab
	v_fma_f32 v21, v20, v21, 0.5
	v_fma_f32 v21, v20, v21, 1.0
	v_mul_f32_e64 v24, v21, -v20
	s_andn2_saveexec_b64 s[2:3], s[2:3]
	v_mul_f32_e32 v20, 0x3fb8aa3b, v20
	v_exp_f32_e32 v20, v20
	s_nop 0
	v_sub_f32_e32 v24, 1.0, v20
	s_or_b64 exec, exec, s[2:3]
	v_or_b32_e32 v20, 50, v66
	v_ashrrev_i32_e32 v21, 31, v20
	v_lshlrev_b64 v[20:21], 10, v[20:21]
	v_lshl_add_u64 v[26:27], v[20:21], 0, v[64:65]
	v_lshl_add_u64 v[22:23], v[26:27], 1, s[40:41]
	ds_read_u16 v25, v178 offset:7200
	v_add_f32_e32 v15, v15, v83
	v_mul_f32_e32 v15, 0xbfb8aa3b, v15
	v_add_f32_e32 v10, v10, v82
	v_exp_f32_e32 v15, v15
	v_mul_f32_e32 v10, 0xbfb8aa3b, v10
	v_exp_f32_e32 v10, v10
	v_max_f32_e32 v24, v24, v24
	v_add_f32_e32 v15, 1.0, v15
	v_rcp_f32_e32 v15, v15
	v_add_f32_e32 v10, 1.0, v10
	v_max_f32_e32 v24, 0, v24
	v_rcp_f32_e32 v29, v10
	v_sqrt_f32_e32 v28, v24
	v_mul_f32_e32 v24, v15, v84
	v_add_f32_e32 v10, v24, v24
	v_lshl_add_u64 v[26:27], v[26:27], 2, s[42:43]
	v_cmp_ngt_f32_e32 vcc, s9, v10
	s_waitcnt lgkmcnt(0)
;   __host__ __device__ __forceinline__ bf16_t* XC() const { return (bf16_t*)(wsl() + OFF_FFN); }
; __device__ __forceinline__ float bf2f(bf16_t h) { return __uint_as_float(((uint32_t)h) << 16); }
; __device__ __forceinline__ uint32_t pack2(float a, float b) { uint32_t r; asm("v_cvt_pk_bf16_f32 %0, %1, %2" : "=v"(r) : "v"(a), "v"(b)); return r; }
; __device__ __forceinline__ float sigmoidf_(float x) { return __builtin_amdgcn_rcpf(1.0f + __expf(-x)); }
; template <int EPI>
; __device__ __forceinline__ void gemm_tile(const Params& p, const EpiArgs& ea, const bf16_t* __restrict__ A, int lda,
;                                           const bf16_t* __restrict__ Bt, int K, int m0, int n0, char* smem) {
;     ...
;       for (int nh = 0; nh < 2; ++nh) {
;         int ch = (n0 >> 1) + wn * 32 + nh * 16 + fr;
;         float ba = p.lru_b_a[ea.dir * 1024 + ch], bx = p.lru_b_x[ea.dir * 1024 + ch];
;         float sp8 = -8.0f * log1pf(__expf(-p.lru_lam[ea.dir * 1024 + ch]));
; #pragma unroll
;         for (int j = 0; j < 4; ++j) {
;           float r = sigmoidf_(acc[mi][nh * 2][j] + ba);
;           float ig = sigmoidf_(acc[mi][nh * 2 + 1][j] + bx);
;           float la = r * sp8;
;           float x2 = 2.0f * la;
;           float poly = -x2 * (1.0f + x2 * (0.5f + x2 * (0.16666667f + x2 * (0.041666668f + x2 * (0.008333334f + x2 * 0.0013888889f)))));
;           float em = (x2 < -0.3f) ? (1.0f - __expf(x2)) : poly;
;           float u = bf2f(p.XC()[(size_t)(r0 + j) * D + ch]);
;           float inp = __builtin_amdgcn_sqrtf(fmaxf(em, 0.0f)) * (ig * u);
;           ea.outu[(size_t)(r0 + j) * D + ch] = pack2(la, inp);
;         }
;       }
	v_lshlrev_b32_e32 v15, 16, v25
	v_mul_f32_e32 v15, v29, v15
	v_mul_f32_e32 v15, v28, v15
	v_cvt_pk_bf16_f32 v14, v14, v15
	v_mov_b32_e32 v215, v14
	s_and_saveexec_b64 s[2:3], vcc
	s_xor_b64 s[2:3], exec, s[2:3]
	v_fmamk_f32 v14, v10, 0x3ab60b61, v169
	v_fmaak_f32 v14, v10, v14, 0x3d2aaaab
	v_fmaak_f32 v14, v10, v14, 0x3e2aaaab
	v_fma_f32 v14, v10, v14, 0.5
	v_fma_f32 v14, v10, v14, 1.0
	v_mul_f32_e64 v25, v14, -v10
	s_andn2_saveexec_b64 s[2:3], s[2:3]
	v_mul_f32_e32 v10, 0x3fb8aa3b, v10
	v_exp_f32_e32 v10, v10
	s_nop 0
	v_sub_f32_e32 v25, 1.0, v10
	s_or_b64 exec, exec, s[2:3]
	v_add_f32_e32 v10, v11, v82
	v_mul_f32_e32 v10, 0xbfb8aa3b, v10
	v_exp_f32_e32 v10, v10
	v_add_f32_e32 v4, v4, v74
	v_mul_f32_e32 v4, 0xbfb8aa3b, v4
	v_exp_f32_e32 v4, v4
	v_add_f32_e32 v10, 1.0, v10
	v_rcp_f32_e32 v28, v10
	v_or_b32_e32 v10, 51, v66
	v_ashrrev_i32_e32 v11, 31, v10
	v_lshlrev_b64 v[10:11], 10, v[10:11]
	v_lshl_add_u64 v[26:27], v[10:11], 0, v[64:65]
	v_lshl_add_u64 v[14:15], v[26:27], 1, s[40:41]
	ds_read_u16 v29, v178 offset:7344
	v_max_f32_e32 v25, v25, v25
	v_max_f32_e32 v25, 0, v25
	v_sqrt_f32_e32 v25, v25
	v_add_f32_e32 v4, 1.0, v4
	v_rcp_f32_e32 v4, v4
	s_waitcnt lgkmcnt(0)
	v_lshlrev_b32_e32 v29, 16, v29
	v_mul_f32_e32 v28, v28, v29
	v_mul_f32_e32 v25, v25, v28
	v_cvt_pk_bf16_f32 v28, v24, v25
	v_lshl_add_u64 v[24:25], v[26:27], 2, s[42:43]
	v_mul_f32_e32 v4, v4, v72
	v_mov_b32_e32 v235, v28
	v_add_f32_e32 v24, v4, v4
	v_cmp_ngt_f32_e32 vcc, s9, v24
	s_and_saveexec_b64 s[2:3], vcc
	s_xor_b64 s[2:3], exec, s[2:3]
	v_fmamk_f32 v25, v24, 0x3ab60b61, v169
	v_fmaak_f32 v25, v24, v25, 0x3d2aaaab
	v_fmaak_f32 v25, v24, v25, 0x3e2aaaab
	v_fma_f32 v25, v24, v25, 0.5
	v_fma_f32 v25, v24, v25, 1.0
	v_mul_f32_e64 v25, v25, -v24
	s_andn2_saveexec_b64 s[2:3], s[2:3]
	v_mul_f32_e32 v24, 0x3fb8aa3b, v24
	v_exp_f32_e32 v24, v24
	s_nop 0
	v_sub_f32_e32 v25, 1.0, v24
	s_or_b64 exec, exec, s[2:3]
	ds_read_u16 v18, v178 offset:6944
	v_add_f32_e32 v5, v5, v74
	v_add_f32_e32 v0, v0, v67
	v_mul_f32_e32 v5, 0xbfb8aa3b, v5
	v_mul_f32_e32 v0, 0xbfb8aa3b, v0
	v_exp_f32_e32 v5, v5
	v_exp_f32_e32 v0, v0
	v_max_f32_e32 v19, v25, v25
	v_max_f32_e32 v19, 0, v19
	v_add_f32_e32 v5, 1.0, v5
	v_rcp_f32_e32 v5, v5
	v_add_f32_e32 v0, 1.0, v0
	v_rcp_f32_e32 v24, v0
	v_sqrt_f32_e32 v19, v19
	v_mul_f32_e32 v0, v5, v72
	v_lshl_add_u64 v[16:17], v[16:17], 0, v[52:53]
	v_add_f32_e32 v5, v0, v0
	v_lshl_add_u64 v[16:17], v[16:17], 2, s[42:43]
	v_cmp_ngt_f32_e32 vcc, s9, v5
	s_waitcnt lgkmcnt(0)
	v_lshlrev_b32_e32 v18, 16, v18
	v_mul_f32_e32 v18, v24, v18
	v_mul_f32_e32 v18, v19, v18
	v_cvt_pk_bf16_f32 v4, v4, v18
	v_mov_b32_e32 v236, v4
	s_and_saveexec_b64 s[2:3], vcc
	s_xor_b64 s[2:3], exec, s[2:3]
	v_fmamk_f32 v4, v5, 0x3ab60b61, v169
	v_fmaak_f32 v4, v5, v4, 0x3d2aaaab
	v_fmaak_f32 v4, v5, v4, 0x3e2aaaab
	v_fma_f32 v4, v5, v4, 0.5
	v_fma_f32 v4, v5, v4, 1.0
	v_mul_f32_e64 v4, v4, -v5
	s_andn2_saveexec_b64 s[2:3], s[2:3]
	v_mul_f32_e32 v4, 0x3fb8aa3b, v5
	v_exp_f32_e32 v4, v4
	s_nop 0
	v_sub_f32_e32 v4, 1.0, v4
	s_or_b64 exec, exec, s[2:3]
	ds_read_u16 v5, v178 offset:7088
	v_add_f32_e32 v6, v6, v74
	v_add_f32_e32 v1, v1, v67
	v_mul_f32_e32 v6, 0xbfb8aa3b, v6
	v_mul_f32_e32 v1, 0xbfb8aa3b, v1
	v_exp_f32_e32 v6, v6
	v_exp_f32_e32 v1, v1
	v_max_f32_e32 v4, v4, v4
	v_max_f32_e32 v4, 0, v4
	v_add_f32_e32 v6, 1.0, v6
	v_rcp_f32_e32 v6, v6
	v_add_f32_e32 v1, 1.0, v1
	v_rcp_f32_e32 v13, v1
	v_sqrt_f32_e32 v12, v4
	v_mul_f32_e32 v1, v6, v72
	v_lshl_add_u64 v[8:9], v[8:9], 0, v[52:53]
	v_add_f32_e32 v4, v1, v1
	v_lshl_add_u64 v[8:9], v[8:9], 2, s[42:43]
	v_cmp_ngt_f32_e32 vcc, s9, v4
	s_waitcnt lgkmcnt(0)
	v_lshlrev_b32_e32 v5, 16, v5
	v_mul_f32_e32 v5, v13, v5
	v_mul_f32_e32 v5, v12, v5
	v_cvt_pk_bf16_f32 v0, v0, v5
	v_mov_b32_e32 v237, v0
	s_and_saveexec_b64 s[2:3], vcc
	s_xor_b64 s[2:3], exec, s[2:3]
	v_fmamk_f32 v0, v4, 0x3ab60b61, v169
	v_fmaak_f32 v0, v4, v0, 0x3d2aaaab
	v_fmaak_f32 v0, v4, v0, 0x3e2aaaab
	v_fma_f32 v0, v4, v0, 0.5
	v_fma_f32 v0, v4, v0, 1.0
	v_mul_f32_e64 v0, v0, -v4
	s_andn2_saveexec_b64 s[2:3], s[2:3]
	v_mul_f32_e32 v0, 0x3fb8aa3b, v4
	v_exp_f32_e32 v0, v0
	s_nop 0
	v_sub_f32_e32 v0, 1.0, v0
	s_or_b64 exec, exec, s[2:3]
	ds_read_u16 v6, v178 offset:7232
	v_add_f32_e32 v7, v7, v74
	v_add_f32_e32 v2, v2, v67
	v_mul_f32_e32 v7, 0xbfb8aa3b, v7
	v_mul_f32_e32 v2, 0xbfb8aa3b, v2
	v_exp_f32_e32 v7, v7
	v_exp_f32_e32 v2, v2
	v_max_f32_e32 v0, v0, v0
	v_max_f32_e32 v0, 0, v0
	v_add_f32_e32 v7, 1.0, v7
	v_rcp_f32_e32 v7, v7
	v_sqrt_f32_e32 v8, v0
	v_add_f32_e32 v0, 1.0, v2
	v_rcp_f32_e32 v9, v0
	v_mul_f32_e32 v0, v7, v72
	v_lshl_add_u64 v[4:5], v[20:21], 0, v[52:53]
	v_add_f32_e32 v2, v0, v0
	v_lshl_add_u64 v[4:5], v[4:5], 2, s[42:43]
	v_cmp_ngt_f32_e32 vcc, s9, v2
	s_waitcnt lgkmcnt(0)
	v_lshlrev_b32_e32 v6, 16, v6
	v_mul_f32_e32 v6, v9, v6
	v_mul_f32_e32 v6, v8, v6
	v_cvt_pk_bf16_f32 v1, v1, v6
	v_mov_b32_e32 v238, v1
	s_and_saveexec_b64 s[2:3], vcc
	s_xor_b64 s[2:3], exec, s[2:3]
	v_fmamk_f32 v1, v2, 0x3ab60b61, v169
	v_fmaak_f32 v1, v2, v1, 0x3d2aaaab
	v_fmaak_f32 v1, v2, v1, 0x3e2aaaab
	v_fma_f32 v1, v2, v1, 0.5
	v_fma_f32 v1, v2, v1, 1.0
	v_mul_f32_e64 v1, v1, -v2
	s_andn2_saveexec_b64 s[2:3], s[2:3]
	v_mul_f32_e32 v1, 0x3fb8aa3b, v2
	v_exp_f32_e32 v1, v1
	s_nop 0
	v_sub_f32_e32 v1, 1.0, v1
	s_or_b64 exec, exec, s[2:3]
	ds_read_u16 v4, v178 offset:7376
	v_add_f32_e32 v2, v3, v67
	v_mul_f32_e32 v2, 0xbfb8aa3b, v2
	v_exp_f32_e32 v5, v2
	v_max_f32_e32 v1, v1, v1
	v_max_f32_e32 v1, 0, v1
	v_sqrt_f32_e32 v1, v1
	v_add_f32_e32 v5, 1.0, v5
	v_rcp_f32_e32 v5, v5
	v_lshl_add_u64 v[2:3], v[10:11], 0, v[52:53]
	v_lshl_add_u64 v[2:3], v[2:3], 2, s[42:43]
	s_waitcnt lgkmcnt(0)
;   __host__ __device__ __forceinline__ bf16_t* XC() const { return (bf16_t*)(wsl() + OFF_FFN); }
; __device__ __forceinline__ float bf2f(bf16_t h) { return __uint_as_float(((uint32_t)h) << 16); }
; __device__ __forceinline__ uint32_t pack2(float a, float b) { uint32_t r; asm("v_cvt_pk_bf16_f32 %0, %1, %2" : "=v"(r) : "v"(a), "v"(b)); return r; }
; template <int EPI>
; __device__ __forceinline__ void gemm_tile(const Params& p, const EpiArgs& ea, const bf16_t* __restrict__ A, int lda,
;                                           const bf16_t* __restrict__ Bt, int K, int m0, int n0, char* smem) {
;     ...
;           float u = bf2f(p.XC()[(size_t)(r0 + j) * D + ch]);
;           float inp = __builtin_amdgcn_sqrtf(fmaxf(em, 0.0f)) * (ig * u);
;           ea.outu[(size_t)(r0 + j) * D + ch] = pack2(la, inp);
	v_lshlrev_b32_e32 v4, 16, v4
	v_mul_f32_e32 v4, v5, v4
	v_mul_f32_e32 v1, v1, v4
	v_cvt_pk_bf16_f32 v0, v0, v1
	v_mov_b32_e32 v239, v0
	v_and_b32_e32 v240, 1, v231
	v_cmp_eq_u32_e64 s[68:69], 0, v240
	v_and_b32_e32 v240, 2, v231
	v_cmp_eq_u32_e64 s[70:71], 0, v240
	v_and_b32_e32 v240, 3, v231
	v_or_b32_e32 v248, v66, v240
	v_lshlrev_b32_e32 v248, 10, v248
	v_and_b32_e32 v241, -4, v64
	v_add_u32_e32 v248, v248, v241
	v_mov_b32_e32 v249, 0
	v_lshl_add_u64 v[248:249], v[248:249], 2, s[42:43]
	s_mov_b64 s[72:73], 0x10000
	v_mov_b32_dpp v240, v190 quad_perm:[1,0,3,2] row_mask:0xf bank_mask:0xf
	v_mov_b32_dpp v241, v189 quad_perm:[1,0,3,2] row_mask:0xf bank_mask:0xf
	v_mov_b32_dpp v242, v192 quad_perm:[1,0,3,2] row_mask:0xf bank_mask:0xf
	v_mov_b32_dpp v243, v191 quad_perm:[1,0,3,2] row_mask:0xf bank_mask:0xf
	v_cndmask_b32_e64 v246, v242, v191, s[68:69]
	v_cndmask_b32_e64 v247, v192, v243, s[68:69]
	v_cndmask_b32_e64 v244, v240, v189, s[68:69]
	v_cndmask_b32_e64 v245, v190, v241, s[68:69]
	v_mov_b32_dpp v240, v246 quad_perm:[2,3,0,1] row_mask:0xf bank_mask:0xf
	v_mov_b32_dpp v241, v247 quad_perm:[2,3,0,1] row_mask:0xf bank_mask:0xf
	v_mov_b32_dpp v242, v244 quad_perm:[2,3,0,1] row_mask:0xf bank_mask:0xf
	v_mov_b32_dpp v243, v245 quad_perm:[2,3,0,1] row_mask:0xf bank_mask:0xf
	v_cndmask_b32_e64 v180, v240, v244, s[70:71]
	v_cndmask_b32_e64 v181, v241, v245, s[70:71]
	v_cndmask_b32_e64 v182, v246, v242, s[70:71]
	v_cndmask_b32_e64 v183, v247, v243, s[70:71]
	global_store_dwordx4 v[248:249], v[180:183], off
	v_mov_b32_dpp v240, v194 quad_perm:[1,0,3,2] row_mask:0xf bank_mask:0xf
	v_mov_b32_dpp v241, v193 quad_perm:[1,0,3,2] row_mask:0xf bank_mask:0xf
	v_mov_b32_dpp v242, v196 quad_perm:[1,0,3,2] row_mask:0xf bank_mask:0xf
	v_mov_b32_dpp v243, v195 quad_perm:[1,0,3,2] row_mask:0xf bank_mask:0xf
	v_cndmask_b32_e64 v246, v242, v195, s[68:69]
	v_cndmask_b32_e64 v247, v196, v243, s[68:69]
	v_cndmask_b32_e64 v244, v240, v193, s[68:69]
	v_cndmask_b32_e64 v245, v194, v241, s[68:69]
	v_mov_b32_dpp v240, v246 quad_perm:[2,3,0,1] row_mask:0xf bank_mask:0xf
	v_mov_b32_dpp v241, v247 quad_perm:[2,3,0,1] row_mask:0xf bank_mask:0xf
	v_mov_b32_dpp v242, v244 quad_perm:[2,3,0,1] row_mask:0xf bank_mask:0xf
	v_mov_b32_dpp v243, v245 quad_perm:[2,3,0,1] row_mask:0xf bank_mask:0xf
	v_cndmask_b32_e64 v184, v240, v244, s[70:71]
	v_cndmask_b32_e64 v185, v241, v245, s[70:71]
	v_cndmask_b32_e64 v186, v246, v242, s[70:71]
	v_cndmask_b32_e64 v187, v247, v243, s[70:71]
	global_store_dwordx4 v[248:249], v[184:187], off offset:64
	v_lshl_add_u64 v[248:249], v[248:249], 0, s[72:73]
	v_mov_b32_dpp v240, v198 quad_perm:[1,0,3,2] row_mask:0xf bank_mask:0xf
	v_mov_b32_dpp v241, v197 quad_perm:[1,0,3,2] row_mask:0xf bank_mask:0xf
	v_mov_b32_dpp v242, v200 quad_perm:[1,0,3,2] row_mask:0xf bank_mask:0xf
	v_mov_b32_dpp v243, v199 quad_perm:[1,0,3,2] row_mask:0xf bank_mask:0xf
	v_cndmask_b32_e64 v246, v242, v199, s[68:69]
	v_cndmask_b32_e64 v247, v200, v243, s[68:69]
	v_cndmask_b32_e64 v244, v240, v197, s[68:69]
	v_cndmask_b32_e64 v245, v198, v241, s[68:69]
	v_mov_b32_dpp v240, v246 quad_perm:[2,3,0,1] row_mask:0xf bank_mask:0xf
	v_mov_b32_dpp v241, v247 quad_perm:[2,3,0,1] row_mask:0xf bank_mask:0xf
	v_mov_b32_dpp v242, v244 quad_perm:[2,3,0,1] row_mask:0xf bank_mask:0xf
	v_mov_b32_dpp v243, v245 quad_perm:[2,3,0,1] row_mask:0xf bank_mask:0xf
	v_cndmask_b32_e64 v180, v240, v244, s[70:71]
	v_cndmask_b32_e64 v181, v241, v245, s[70:71]
	v_cndmask_b32_e64 v182, v246, v242, s[70:71]
	v_cndmask_b32_e64 v183, v247, v243, s[70:71]
	global_store_dwordx4 v[248:249], v[180:183], off
	v_mov_b32_dpp v240, v202 quad_perm:[1,0,3,2] row_mask:0xf bank_mask:0xf
	v_mov_b32_dpp v241, v201 quad_perm:[1,0,3,2] row_mask:0xf bank_mask:0xf
	v_mov_b32_dpp v242, v204 quad_perm:[1,0,3,2] row_mask:0xf bank_mask:0xf
	v_mov_b32_dpp v243, v203 quad_perm:[1,0,3,2] row_mask:0xf bank_mask:0xf
	v_cndmask_b32_e64 v246, v242, v203, s[68:69]
	v_cndmask_b32_e64 v247, v204, v243, s[68:69]
	v_cndmask_b32_e64 v244, v240, v201, s[68:69]
	v_cndmask_b32_e64 v245, v202, v241, s[68:69]
	v_mov_b32_dpp v240, v246 quad_perm:[2,3,0,1] row_mask:0xf bank_mask:0xf
	v_mov_b32_dpp v241, v247 quad_perm:[2,3,0,1] row_mask:0xf bank_mask:0xf
	v_mov_b32_dpp v242, v244 quad_perm:[2,3,0,1] row_mask:0xf bank_mask:0xf
	v_mov_b32_dpp v243, v245 quad_perm:[2,3,0,1] row_mask:0xf bank_mask:0xf
;   __host__ __device__ __forceinline__ bf16_t* XC() const { return (bf16_t*)(wsl() + OFF_FFN); }
; __device__ __forceinline__ float bf2f(bf16_t h) { return __uint_as_float(((uint32_t)h) << 16); }
; __device__ __forceinline__ uint32_t pack2(float a, float b) { uint32_t r; asm("v_cvt_pk_bf16_f32 %0, %1, %2" : "=v"(r) : "v"(a), "v"(b)); return r; }
; template <int EPI>
; __device__ __forceinline__ void gemm_tile(const Params& p, const EpiArgs& ea, const bf16_t* __restrict__ A, int lda,
;                                           const bf16_t* __restrict__ Bt, int K, int m0, int n0, char* smem) {
;     ...
;           float u = bf2f(p.XC()[(size_t)(r0 + j) * D + ch]);
;           float inp = __builtin_amdgcn_sqrtf(fmaxf(em, 0.0f)) * (ig * u);
;           ea.outu[(size_t)(r0 + j) * D + ch] = pack2(la, inp);
	v_cndmask_b32_e64 v184, v240, v244, s[70:71]
	v_cndmask_b32_e64 v185, v241, v245, s[70:71]
	v_cndmask_b32_e64 v186, v246, v242, s[70:71]
	v_cndmask_b32_e64 v187, v247, v243, s[70:71]
	global_store_dwordx4 v[248:249], v[184:187], off offset:64
	v_lshl_add_u64 v[248:249], v[248:249], 0, s[72:73]
	v_mov_b32_dpp v240, v206 quad_perm:[1,0,3,2] row_mask:0xf bank_mask:0xf
	v_mov_b32_dpp v241, v205 quad_perm:[1,0,3,2] row_mask:0xf bank_mask:0xf
	v_mov_b32_dpp v242, v208 quad_perm:[1,0,3,2] row_mask:0xf bank_mask:0xf
	v_mov_b32_dpp v243, v207 quad_perm:[1,0,3,2] row_mask:0xf bank_mask:0xf
	v_cndmask_b32_e64 v246, v242, v207, s[68:69]
	v_cndmask_b32_e64 v247, v208, v243, s[68:69]
	v_cndmask_b32_e64 v244, v240, v205, s[68:69]
	v_cndmask_b32_e64 v245, v206, v241, s[68:69]
	v_mov_b32_dpp v240, v246 quad_perm:[2,3,0,1] row_mask:0xf bank_mask:0xf
	v_mov_b32_dpp v241, v247 quad_perm:[2,3,0,1] row_mask:0xf bank_mask:0xf
	v_mov_b32_dpp v242, v244 quad_perm:[2,3,0,1] row_mask:0xf bank_mask:0xf
	v_mov_b32_dpp v243, v245 quad_perm:[2,3,0,1] row_mask:0xf bank_mask:0xf
	v_cndmask_b32_e64 v180, v240, v244, s[70:71]
	v_cndmask_b32_e64 v181, v241, v245, s[70:71]
	v_cndmask_b32_e64 v182, v246, v242, s[70:71]
	v_cndmask_b32_e64 v183, v247, v243, s[70:71]
	global_store_dwordx4 v[248:249], v[180:183], off
	v_mov_b32_dpp v240, v210 quad_perm:[1,0,3,2] row_mask:0xf bank_mask:0xf
	v_mov_b32_dpp v241, v209 quad_perm:[1,0,3,2] row_mask:0xf bank_mask:0xf
	v_mov_b32_dpp v242, v212 quad_perm:[1,0,3,2] row_mask:0xf bank_mask:0xf
	v_mov_b32_dpp v243, v211 quad_perm:[1,0,3,2] row_mask:0xf bank_mask:0xf
	v_cndmask_b32_e64 v246, v242, v211, s[68:69]
	v_cndmask_b32_e64 v247, v212, v243, s[68:69]
	v_cndmask_b32_e64 v244, v240, v209, s[68:69]
	v_cndmask_b32_e64 v245, v210, v241, s[68:69]
	v_mov_b32_dpp v240, v246 quad_perm:[2,3,0,1] row_mask:0xf bank_mask:0xf
	v_mov_b32_dpp v241, v247 quad_perm:[2,3,0,1] row_mask:0xf bank_mask:0xf
	v_mov_b32_dpp v242, v244 quad_perm:[2,3,0,1] row_mask:0xf bank_mask:0xf
	v_mov_b32_dpp v243, v245 quad_perm:[2,3,0,1] row_mask:0xf bank_mask:0xf
	v_cndmask_b32_e64 v184, v240, v244, s[70:71]
	v_cndmask_b32_e64 v185, v241, v245, s[70:71]
	v_cndmask_b32_e64 v186, v246, v242, s[70:71]
	v_cndmask_b32_e64 v187, v247, v243, s[70:71]
	global_store_dwordx4 v[248:249], v[184:187], off offset:64
	v_lshl_add_u64 v[248:249], v[248:249], 0, s[72:73]
	v_mov_b32_dpp v240, v214 quad_perm:[1,0,3,2] row_mask:0xf bank_mask:0xf
	v_mov_b32_dpp v241, v213 quad_perm:[1,0,3,2] row_mask:0xf bank_mask:0xf
	v_mov_b32_dpp v242, v235 quad_perm:[1,0,3,2] row_mask:0xf bank_mask:0xf
	v_mov_b32_dpp v243, v215 quad_perm:[1,0,3,2] row_mask:0xf bank_mask:0xf
	v_cndmask_b32_e64 v246, v242, v215, s[68:69]
	v_cndmask_b32_e64 v247, v235, v243, s[68:69]
	v_cndmask_b32_e64 v244, v240, v213, s[68:69]
	v_cndmask_b32_e64 v245, v214, v241, s[68:69]
	v_mov_b32_dpp v240, v246 quad_perm:[2,3,0,1] row_mask:0xf bank_mask:0xf
	v_mov_b32_dpp v241, v247 quad_perm:[2,3,0,1] row_mask:0xf bank_mask:0xf
	v_mov_b32_dpp v242, v244 quad_perm:[2,3,0,1] row_mask:0xf bank_mask:0xf
	v_mov_b32_dpp v243, v245 quad_perm:[2,3,0,1] row_mask:0xf bank_mask:0xf
	v_cndmask_b32_e64 v180, v240, v244, s[70:71]
	v_cndmask_b32_e64 v181, v241, v245, s[70:71]
	v_cndmask_b32_e64 v182, v246, v242, s[70:71]
	v_cndmask_b32_e64 v183, v247, v243, s[70:71]
	global_store_dwordx4 v[248:249], v[180:183], off
	v_mov_b32_dpp v240, v237 quad_perm:[1,0,3,2] row_mask:0xf bank_mask:0xf
	v_mov_b32_dpp v241, v236 quad_perm:[1,0,3,2] row_mask:0xf bank_mask:0xf
	v_mov_b32_dpp v242, v239 quad_perm:[1,0,3,2] row_mask:0xf bank_mask:0xf
	v_mov_b32_dpp v243, v238 quad_perm:[1,0,3,2] row_mask:0xf bank_mask:0xf
	v_cndmask_b32_e64 v246, v242, v238, s[68:69]
	v_cndmask_b32_e64 v247, v239, v243, s[68:69]
	v_cndmask_b32_e64 v244, v240, v236, s[68:69]
	v_cndmask_b32_e64 v245, v237, v241, s[68:69]
	v_mov_b32_dpp v240, v246 quad_perm:[2,3,0,1] row_mask:0xf bank_mask:0xf
	v_mov_b32_dpp v241, v247 quad_perm:[2,3,0,1] row_mask:0xf bank_mask:0xf
	v_mov_b32_dpp v242, v244 quad_perm:[2,3,0,1] row_mask:0xf bank_mask:0xf
	v_mov_b32_dpp v243, v245 quad_perm:[2,3,0,1] row_mask:0xf bank_mask:0xf
	v_cndmask_b32_e64 v184, v240, v244, s[70:71]
	v_cndmask_b32_e64 v185, v241, v245, s[70:71]
	v_cndmask_b32_e64 v186, v246, v242, s[70:71]
	v_cndmask_b32_e64 v187, v247, v243, s[70:71]
	global_store_dwordx4 v[248:249], v[184:187], off offset:64
	s_barrier
	s_mov_b32 s9, 0
